# first K-loop iteration of every tile peeled: first MFMA into each accumulator takes inline 0 as srcC, the 128-mov accumulator zeroing in the loop preheader deleted (7 GEMM tile loops); on top of saddr
# speedup vs baseline: 1.0037x; 1.0010x over previous
.Lkz_0:
	s_and_b64 s[0:1], s[38:39], exec
	s_cselect_b32 s0, s29, s41
	s_cselect_b32 s1, s28, s40
	s_cselect_b32 s5, s31, s3
	s_cselect_b32 s7, s30, s2
	s_add_u32 s14, s40, 0x100
	s_addc_u32 s15, s41, 0
	s_add_u32 s25, s2, 0x100
	s_addc_u32 s27, s3, 0
	s_mov_b32 s2, 0
	v_add_u32_e32 v168, 0x10000, v162
	v_add_u32_e32 v184, 0x14000, v162
	ds_read_b128 v[150:153], v168
	ds_read_b128 v[154:157], v168 offset:1024
	ds_read_b128 v[164:167], v168 offset:2048
	ds_read_b128 v[168:171], v168 offset:3072
	ds_read_b128 v[172:175], v184
	ds_read_b128 v[176:179], v184 offset:1024
	ds_read_b128 v[180:183], v184 offset:2048
	ds_read_b128 v[184:187], v184 offset:3072
	s_add_i32 s33, s2, 2
	s_cmp_eq_u32 s72, s2
	s_cselect_b32 s42, s1, s14
	s_cselect_b32 s43, s0, s15
	s_cselect_b32 s40, s7, s25
	s_cselect_b32 s41, s5, s27
	s_add_u32 s2, s42, 0x80
	s_addc_u32 s3, s43, 0
	ds_read_b128 v[188:191], v163
	ds_read_b128 v[192:195], v163 offset:1024
	ds_read_b128 v[206:209], v163 offset:2048
	ds_read_b128 v[210:213], v163 offset:3072
	ds_read_b128 v[214:217], v163 offset:4096
	ds_read_b128 v[226:229], v163 offset:5120
	ds_read_b128 v[230:233], v163 offset:6144
	ds_read_b128 v[234:237], v163 offset:7168
	s_add_u32 s34, s14, 0x7ff80
	s_addc_u32 s35, s15, 0
	s_mov_b32 m0, s73
	s_nop 0
	global_load_lds_dwordx4 v149, s[34:35]
	s_mov_b32 m0, s75
	s_nop 0
	global_load_lds_dwordx4 v159, s[34:35]
	s_waitcnt vmcnt(8)
	s_waitcnt lgkmcnt(0)
	s_barrier
	s_setprio 1
	s_waitcnt lgkmcnt(7)
	v_mfma_f32_16x16x32_bf16 v[128:131], v[150:153], v[188:191], 0
	v_mfma_f32_16x16x32_bf16 v[124:127], v[164:167], v[188:191], 0
	s_waitcnt lgkmcnt(5)
	v_mfma_f32_16x16x32_bf16 v[112:115], v[150:153], v[206:209], 0
	v_mfma_f32_16x16x32_bf16 v[108:111], v[164:167], v[206:209], 0
	s_waitcnt lgkmcnt(3)
	v_mfma_f32_16x16x32_bf16 v[96:99], v[150:153], v[214:217], 0
	v_mfma_f32_16x16x32_bf16 v[92:95], v[164:167], v[214:217], 0
	s_waitcnt lgkmcnt(1)
	v_mfma_f32_16x16x32_bf16 v[80:83], v[150:153], v[230:233], 0
	v_mfma_f32_16x16x32_bf16 v[76:79], v[164:167], v[230:233], 0
	v_mfma_f32_16x16x32_bf16 v[128:131], v[154:157], v[192:195], v[128:131]
	v_mfma_f32_16x16x32_bf16 v[124:127], v[168:171], v[192:195], v[124:127]
	v_mfma_f32_16x16x32_bf16 v[112:115], v[154:157], v[210:213], v[112:115]
	v_mfma_f32_16x16x32_bf16 v[108:111], v[168:171], v[210:213], v[108:111]
	v_mfma_f32_16x16x32_bf16 v[96:99], v[154:157], v[226:229], v[96:99]
	v_mfma_f32_16x16x32_bf16 v[92:95], v[168:171], v[226:229], v[92:95]
	s_waitcnt lgkmcnt(0)
	v_mfma_f32_16x16x32_bf16 v[80:83], v[154:157], v[234:237], v[80:83]
	v_mfma_f32_16x16x32_bf16 v[76:79], v[168:171], v[234:237], v[76:79]
	s_setprio 0
	s_setprio 1
	v_mfma_f32_16x16x32_bf16 v[120:123], v[172:175], v[188:191], 0
	v_mfma_f32_16x16x32_bf16 v[116:119], v[180:183], v[188:191], 0
	v_mfma_f32_16x16x32_bf16 v[104:107], v[172:175], v[206:209], 0
	v_mfma_f32_16x16x32_bf16 v[100:103], v[180:183], v[206:209], 0
	v_mfma_f32_16x16x32_bf16 v[88:91], v[172:175], v[214:217], 0
	v_mfma_f32_16x16x32_bf16 v[84:87], v[180:183], v[214:217], 0
	v_mfma_f32_16x16x32_bf16 v[72:75], v[172:175], v[230:233], 0
	v_mfma_f32_16x16x32_bf16 v[68:71], v[180:183], v[230:233], 0
	v_mfma_f32_16x16x32_bf16 v[120:123], v[176:179], v[192:195], v[120:123]
	v_mfma_f32_16x16x32_bf16 v[116:119], v[184:187], v[192:195], v[116:119]
	v_mfma_f32_16x16x32_bf16 v[104:107], v[176:179], v[210:213], v[104:107]
	v_mfma_f32_16x16x32_bf16 v[100:103], v[184:187], v[210:213], v[100:103]
	v_mfma_f32_16x16x32_bf16 v[88:91], v[176:179], v[226:229], v[88:91]
	v_mfma_f32_16x16x32_bf16 v[84:87], v[184:187], v[226:229], v[84:87]
	v_mfma_f32_16x16x32_bf16 v[72:75], v[176:179], v[234:237], v[72:75]
	v_mfma_f32_16x16x32_bf16 v[68:71], v[184:187], v[234:237], v[68:71]
	s_setprio 0
	s_barrier
	ds_read_b128 v[188:191], v163 offset:16384
	ds_read_b128 v[192:195], v163 offset:17408
	ds_read_b128 v[206:209], v163 offset:18432
	ds_read_b128 v[210:213], v163 offset:19456
	ds_read_b128 v[214:217], v163 offset:20480
	ds_read_b128 v[226:229], v163 offset:21504
	ds_read_b128 v[230:233], v163 offset:22528
	ds_read_b128 v[234:237], v163 offset:23552
	s_mov_b32 m0, s55
	s_nop 0
	global_load_lds_dwordx4 v158, s[40:41]
	s_mov_b32 m0, s56
	s_nop 0
	global_load_lds_dwordx4 v160, s[40:41]
	s_add_u32 s34, s40, 0x80000
	s_addc_u32 s35, s41, 0
	s_mov_b32 m0, s57
	s_nop 0
	global_load_lds_dwordx4 v158, s[34:35]
	s_mov_b32 m0, s58
	s_nop 0
	global_load_lds_dwordx4 v160, s[34:35]
	s_mov_b32 m0, s54
	s_nop 0
	global_load_lds_dwordx4 v149, s[42:43]
	s_mov_b32 m0, s59
	s_nop 0
	global_load_lds_dwordx4 v159, s[42:43]
	s_waitcnt vmcnt(8)
	s_waitcnt lgkmcnt(0)
	s_barrier
	s_setprio 1
	s_waitcnt lgkmcnt(7)
	v_mfma_f32_16x16x32_bf16 v[64:67], v[150:153], v[188:191], 0
	v_mfma_f32_16x16x32_bf16 v[60:63], v[164:167], v[188:191], 0
	s_waitcnt lgkmcnt(5)
	v_mfma_f32_16x16x32_bf16 v[48:51], v[150:153], v[206:209], 0
	v_mfma_f32_16x16x32_bf16 v[44:47], v[164:167], v[206:209], 0
	s_waitcnt lgkmcnt(3)
	v_mfma_f32_16x16x32_bf16 v[32:35], v[150:153], v[214:217], 0
	v_mfma_f32_16x16x32_bf16 v[28:31], v[164:167], v[214:217], 0
	s_waitcnt lgkmcnt(1)
	v_mfma_f32_16x16x32_bf16 v[16:19], v[150:153], v[230:233], 0
	v_mfma_f32_16x16x32_bf16 v[12:15], v[164:167], v[230:233], 0
	v_mfma_f32_16x16x32_bf16 v[64:67], v[154:157], v[192:195], v[64:67]
	v_mfma_f32_16x16x32_bf16 v[60:63], v[168:171], v[192:195], v[60:63]
	v_mfma_f32_16x16x32_bf16 v[48:51], v[154:157], v[210:213], v[48:51]
	v_mfma_f32_16x16x32_bf16 v[44:47], v[168:171], v[210:213], v[44:47]
	v_mfma_f32_16x16x32_bf16 v[32:35], v[154:157], v[226:229], v[32:35]
	v_mfma_f32_16x16x32_bf16 v[28:31], v[168:171], v[226:229], v[28:31]
	s_waitcnt lgkmcnt(0)
	v_mfma_f32_16x16x32_bf16 v[16:19], v[154:157], v[234:237], v[16:19]
	v_mfma_f32_16x16x32_bf16 v[12:15], v[168:171], v[234:237], v[12:15]
	s_setprio 0
	s_setprio 1
	v_mfma_f32_16x16x32_bf16 v[56:59], v[172:175], v[188:191], 0
	v_mfma_f32_16x16x32_bf16 v[52:55], v[180:183], v[188:191], 0
	v_mfma_f32_16x16x32_bf16 v[40:43], v[172:175], v[206:209], 0
	v_mfma_f32_16x16x32_bf16 v[36:39], v[180:183], v[206:209], 0
	v_mfma_f32_16x16x32_bf16 v[24:27], v[172:175], v[214:217], 0
	v_mfma_f32_16x16x32_bf16 v[20:23], v[180:183], v[214:217], 0
	v_mfma_f32_16x16x32_bf16 v[8:11], v[172:175], v[230:233], 0
	v_mfma_f32_16x16x32_bf16 v[4:7], v[180:183], v[230:233], 0
	v_mfma_f32_16x16x32_bf16 v[56:59], v[176:179], v[192:195], v[56:59]
	v_mfma_f32_16x16x32_bf16 v[52:55], v[184:187], v[192:195], v[52:55]
	v_mfma_f32_16x16x32_bf16 v[40:43], v[176:179], v[210:213], v[40:43]
	v_mfma_f32_16x16x32_bf16 v[36:39], v[184:187], v[210:213], v[36:39]
	v_mfma_f32_16x16x32_bf16 v[24:27], v[176:179], v[226:229], v[24:27]
	v_mfma_f32_16x16x32_bf16 v[20:23], v[184:187], v[226:229], v[20:23]
	v_mfma_f32_16x16x32_bf16 v[8:11], v[176:179], v[234:237], v[8:11]
	v_mfma_f32_16x16x32_bf16 v[4:7], v[184:187], v[234:237], v[4:7]
	s_setprio 0
	s_barrier
	v_add_u32_e32 v168, 0x18000, v162
	v_add_u32_e32 v184, 0x1c000, v162
	ds_read_b128 v[150:153], v168
	ds_read_b128 v[154:157], v168 offset:1024
	ds_read_b128 v[164:167], v168 offset:2048
	ds_read_b128 v[168:171], v168 offset:3072
	ds_read_b128 v[172:175], v184
	ds_read_b128 v[176:179], v184 offset:1024
	ds_read_b128 v[180:183], v184 offset:2048
	ds_read_b128 v[184:187], v184 offset:3072
	ds_read_b128 v[188:191], v163 offset:32768
	ds_read_b128 v[192:195], v163 offset:33792
	ds_read_b128 v[206:209], v163 offset:34816
	ds_read_b128 v[210:213], v163 offset:35840
	ds_read_b128 v[214:217], v163 offset:36864
	ds_read_b128 v[226:229], v163 offset:37888
	ds_read_b128 v[230:233], v163 offset:38912
	ds_read_b128 v[234:237], v163 offset:39936
	s_add_u32 s34, s42, 0x80000
	s_addc_u32 s35, s43, 0
	s_mov_b32 m0, s60
	s_nop 0
	global_load_lds_dwordx4 v149, s[34:35]
	s_mov_b32 m0, s61
	s_nop 0
	global_load_lds_dwordx4 v159, s[34:35]
	s_waitcnt vmcnt(8)
	s_waitcnt lgkmcnt(0)
	s_barrier
	s_setprio 1
	s_waitcnt lgkmcnt(7)
	v_mfma_f32_16x16x32_bf16 v[128:131], v[150:153], v[188:191], v[128:131]
	v_mfma_f32_16x16x32_bf16 v[124:127], v[164:167], v[188:191], v[124:127]
	s_waitcnt lgkmcnt(5)
	v_mfma_f32_16x16x32_bf16 v[112:115], v[150:153], v[206:209], v[112:115]
	v_mfma_f32_16x16x32_bf16 v[108:111], v[164:167], v[206:209], v[108:111]
	s_waitcnt lgkmcnt(3)
	v_mfma_f32_16x16x32_bf16 v[96:99], v[150:153], v[214:217], v[96:99]
	v_mfma_f32_16x16x32_bf16 v[92:95], v[164:167], v[214:217], v[92:95]
	s_waitcnt lgkmcnt(1)
	v_mfma_f32_16x16x32_bf16 v[80:83], v[150:153], v[230:233], v[80:83]
	v_mfma_f32_16x16x32_bf16 v[76:79], v[164:167], v[230:233], v[76:79]
	v_mfma_f32_16x16x32_bf16 v[128:131], v[154:157], v[192:195], v[128:131]
	v_mfma_f32_16x16x32_bf16 v[124:127], v[168:171], v[192:195], v[124:127]
	v_mfma_f32_16x16x32_bf16 v[112:115], v[154:157], v[210:213], v[112:115]
	v_mfma_f32_16x16x32_bf16 v[108:111], v[168:171], v[210:213], v[108:111]
	v_mfma_f32_16x16x32_bf16 v[96:99], v[154:157], v[226:229], v[96:99]
	v_mfma_f32_16x16x32_bf16 v[92:95], v[168:171], v[226:229], v[92:95]
	s_waitcnt lgkmcnt(0)
	v_mfma_f32_16x16x32_bf16 v[80:83], v[154:157], v[234:237], v[80:83]
	v_mfma_f32_16x16x32_bf16 v[76:79], v[168:171], v[234:237], v[76:79]
	s_setprio 0
	s_setprio 1
	v_mfma_f32_16x16x32_bf16 v[120:123], v[172:175], v[188:191], v[120:123]
	v_mfma_f32_16x16x32_bf16 v[116:119], v[180:183], v[188:191], v[116:119]
	v_mfma_f32_16x16x32_bf16 v[104:107], v[172:175], v[206:209], v[104:107]
	v_mfma_f32_16x16x32_bf16 v[100:103], v[180:183], v[206:209], v[100:103]
	v_mfma_f32_16x16x32_bf16 v[88:91], v[172:175], v[214:217], v[88:91]
	v_mfma_f32_16x16x32_bf16 v[84:87], v[180:183], v[214:217], v[84:87]
	v_mfma_f32_16x16x32_bf16 v[72:75], v[172:175], v[230:233], v[72:75]
	v_mfma_f32_16x16x32_bf16 v[68:71], v[180:183], v[230:233], v[68:71]
	v_mfma_f32_16x16x32_bf16 v[120:123], v[176:179], v[192:195], v[120:123]
	v_mfma_f32_16x16x32_bf16 v[116:119], v[184:187], v[192:195], v[116:119]
	v_mfma_f32_16x16x32_bf16 v[104:107], v[176:179], v[210:213], v[104:107]
	v_mfma_f32_16x16x32_bf16 v[100:103], v[184:187], v[210:213], v[100:103]
	v_mfma_f32_16x16x32_bf16 v[88:91], v[176:179], v[226:229], v[88:91]
	v_mfma_f32_16x16x32_bf16 v[84:87], v[184:187], v[226:229], v[84:87]
	v_mfma_f32_16x16x32_bf16 v[72:75], v[176:179], v[234:237], v[72:75]
	v_mfma_f32_16x16x32_bf16 v[68:71], v[184:187], v[234:237], v[68:71]
	s_setprio 0
	s_barrier
	ds_read_b128 v[188:191], v163 offset:49152
	ds_read_b128 v[192:195], v163 offset:50176
	ds_read_b128 v[206:209], v163 offset:51200
	ds_read_b128 v[210:213], v163 offset:52224
	ds_read_b128 v[214:217], v163 offset:53248
	ds_read_b128 v[226:229], v163 offset:54272
	ds_read_b128 v[230:233], v163 offset:55296
	ds_read_b128 v[234:237], v163 offset:56320
	s_add_u32 s34, s40, 0x80
	s_addc_u32 s35, s41, 0
	s_mov_b32 m0, s66
	s_nop 0
	global_load_lds_dwordx4 v158, s[34:35]
	s_mov_b32 m0, s67
	s_nop 0
	global_load_lds_dwordx4 v160, s[34:35]
	s_add_u32 s34, s40, 0x80080
	s_addc_u32 s35, s41, 0
	s_mov_b32 m0, s70
	s_nop 0
	global_load_lds_dwordx4 v158, s[34:35]
	s_mov_b32 m0, s71
	s_nop 0
	global_load_lds_dwordx4 v160, s[34:35]
	s_mov_b32 m0, s68
	s_nop 0
	global_load_lds_dwordx4 v149, s[2:3]
	s_mov_b32 m0, s69
	s_nop 0
	global_load_lds_dwordx4 v159, s[2:3]
	s_waitcnt vmcnt(8)
	s_waitcnt lgkmcnt(0)
	s_barrier
	s_setprio 1
	s_waitcnt lgkmcnt(7)
	v_mfma_f32_16x16x32_bf16 v[64:67], v[150:153], v[188:191], v[64:67]
	v_mfma_f32_16x16x32_bf16 v[60:63], v[164:167], v[188:191], v[60:63]
	s_waitcnt lgkmcnt(5)
	v_mfma_f32_16x16x32_bf16 v[48:51], v[150:153], v[206:209], v[48:51]
	v_mfma_f32_16x16x32_bf16 v[44:47], v[164:167], v[206:209], v[44:47]
	s_waitcnt lgkmcnt(3)
	v_mfma_f32_16x16x32_bf16 v[32:35], v[150:153], v[214:217], v[32:35]
	v_mfma_f32_16x16x32_bf16 v[28:31], v[164:167], v[214:217], v[28:31]
	s_waitcnt lgkmcnt(1)
	v_mfma_f32_16x16x32_bf16 v[16:19], v[150:153], v[230:233], v[16:19]
	v_mfma_f32_16x16x32_bf16 v[12:15], v[164:167], v[230:233], v[12:15]
	v_mfma_f32_16x16x32_bf16 v[64:67], v[154:157], v[192:195], v[64:67]
	v_mfma_f32_16x16x32_bf16 v[60:63], v[168:171], v[192:195], v[60:63]
	v_mfma_f32_16x16x32_bf16 v[48:51], v[154:157], v[210:213], v[48:51]
	v_mfma_f32_16x16x32_bf16 v[44:47], v[168:171], v[210:213], v[44:47]
	v_mfma_f32_16x16x32_bf16 v[32:35], v[154:157], v[226:229], v[32:35]
	v_mfma_f32_16x16x32_bf16 v[28:31], v[168:171], v[226:229], v[28:31]
	s_waitcnt lgkmcnt(0)
	v_mfma_f32_16x16x32_bf16 v[16:19], v[154:157], v[234:237], v[16:19]
	v_mfma_f32_16x16x32_bf16 v[12:15], v[168:171], v[234:237], v[12:15]
	s_setprio 0
	s_setprio 1
	v_mfma_f32_16x16x32_bf16 v[56:59], v[172:175], v[188:191], v[56:59]
	v_mfma_f32_16x16x32_bf16 v[52:55], v[180:183], v[188:191], v[52:55]
	v_mfma_f32_16x16x32_bf16 v[40:43], v[172:175], v[206:209], v[40:43]
	v_mfma_f32_16x16x32_bf16 v[36:39], v[180:183], v[206:209], v[36:39]
	v_mfma_f32_16x16x32_bf16 v[24:27], v[172:175], v[214:217], v[24:27]
	v_mfma_f32_16x16x32_bf16 v[20:23], v[180:183], v[214:217], v[20:23]
	v_mfma_f32_16x16x32_bf16 v[8:11], v[172:175], v[230:233], v[8:11]
	v_mfma_f32_16x16x32_bf16 v[4:7], v[180:183], v[230:233], v[4:7]
	v_mfma_f32_16x16x32_bf16 v[56:59], v[176:179], v[192:195], v[56:59]
	v_mfma_f32_16x16x32_bf16 v[52:55], v[184:187], v[192:195], v[52:55]
	v_mfma_f32_16x16x32_bf16 v[40:43], v[176:179], v[210:213], v[40:43]
	v_mfma_f32_16x16x32_bf16 v[36:39], v[184:187], v[210:213], v[36:39]
	v_mfma_f32_16x16x32_bf16 v[24:27], v[176:179], v[226:229], v[24:27]
	v_mfma_f32_16x16x32_bf16 v[20:23], v[184:187], v[226:229], v[20:23]
	v_mfma_f32_16x16x32_bf16 v[8:11], v[176:179], v[234:237], v[8:11]
	v_mfma_f32_16x16x32_bf16 v[4:7], v[184:187], v[234:237], v[4:7]
	s_setprio 0
	s_barrier
	s_add_u32 s14, s14, 0x100
	s_addc_u32 s15, s15, 0
	s_add_u32 s25, s25, 0x100
	s_addc_u32 s27, s27, 0
	s_cmp_ge_i32 s33, s65
	s_mov_b32 s2, s33
	s_cbranch_scc0 .LBB0_317
	s_branch .LBB0_318

.Lkz_1:
	s_and_b64 s[48:49], s[4:5], exec
	s_cselect_b32 s27, s31, s43
	s_cselect_b32 s29, s30, s42
	s_cselect_b32 s73, s39, s41
	s_cselect_b32 s74, s38, s40
	s_add_u32 s75, s42, 0x100
	s_addc_u32 s76, s43, 0
	s_add_u32 s77, s40, 0x100
	s_addc_u32 s78, s41, 0
	s_add_u32 s40, s42, 0x20080
	s_addc_u32 s41, s43, 0
	s_mov_b32 s42, 0
	v_add_u32_e32 v150, 0x10000, v136
	v_add_u32_e32 v166, 0x14000, v136
	ds_read_b128 v[138:141], v150
	ds_read_b128 v[142:145], v150 offset:1024
	ds_read_b128 v[146:149], v150 offset:2048
	ds_read_b128 v[150:153], v150 offset:3072
	ds_read_b128 v[154:157], v166
	ds_read_b128 v[158:161], v166 offset:1024
	ds_read_b128 v[162:165], v166 offset:2048
	ds_read_b128 v[166:169], v166 offset:3072
	s_add_i32 s79, s42, 2
	s_cmp_eq_u32 s69, s42
	s_cselect_b32 s50, s29, s75
	s_cselect_b32 s51, s27, s76
	s_cselect_b32 s48, s74, s77
	s_cselect_b32 s49, s73, s78
	s_add_u32 s42, s50, 0x80
	s_addc_u32 s43, s51, 0
	ds_read_b128 v[170:173], v137
	ds_read_b128 v[174:177], v137 offset:1024
	ds_read_b128 v[178:181], v137 offset:2048
	ds_read_b128 v[182:185], v137 offset:3072
	ds_read_b128 v[186:189], v137 offset:4096
	ds_read_b128 v[190:193], v137 offset:5120
	ds_read_b128 v[194:197], v137 offset:6144
	ds_read_b128 v[206:209], v137 offset:7168
	s_mov_b32 m0, s70
	s_nop 0
	global_load_lds_dwordx4 v1, s[40:41]
	s_mov_b32 m0, s71
	s_nop 0
	global_load_lds_dwordx4 v132, s[40:41]
	s_waitcnt vmcnt(8)
	s_waitcnt lgkmcnt(0)
	s_barrier
	s_setprio 1
	s_waitcnt lgkmcnt(7)
	v_mfma_f32_16x16x32_bf16 v[124:127], v[138:141], v[170:173], 0
	v_mfma_f32_16x16x32_bf16 v[128:131], v[146:149], v[170:173], 0
	s_waitcnt lgkmcnt(5)
	v_mfma_f32_16x16x32_bf16 v[112:115], v[138:141], v[178:181], 0
	v_mfma_f32_16x16x32_bf16 v[108:111], v[146:149], v[178:181], 0
	s_waitcnt lgkmcnt(3)
	v_mfma_f32_16x16x32_bf16 v[96:99], v[138:141], v[186:189], 0
	v_mfma_f32_16x16x32_bf16 v[92:95], v[146:149], v[186:189], 0
	s_waitcnt lgkmcnt(1)
	v_mfma_f32_16x16x32_bf16 v[80:83], v[138:141], v[194:197], 0
	v_mfma_f32_16x16x32_bf16 v[76:79], v[146:149], v[194:197], 0
	v_mfma_f32_16x16x32_bf16 v[124:127], v[142:145], v[174:177], v[124:127]
	v_mfma_f32_16x16x32_bf16 v[128:131], v[150:153], v[174:177], v[128:131]
	v_mfma_f32_16x16x32_bf16 v[112:115], v[142:145], v[182:185], v[112:115]
	v_mfma_f32_16x16x32_bf16 v[108:111], v[150:153], v[182:185], v[108:111]
	v_mfma_f32_16x16x32_bf16 v[96:99], v[142:145], v[190:193], v[96:99]
	v_mfma_f32_16x16x32_bf16 v[92:95], v[150:153], v[190:193], v[92:95]
	s_waitcnt lgkmcnt(0)
	v_mfma_f32_16x16x32_bf16 v[80:83], v[142:145], v[206:209], v[80:83]
	v_mfma_f32_16x16x32_bf16 v[76:79], v[150:153], v[206:209], v[76:79]
	s_setprio 0
	s_setprio 1
	v_mfma_f32_16x16x32_bf16 v[120:123], v[154:157], v[170:173], 0
	v_mfma_f32_16x16x32_bf16 v[116:119], v[162:165], v[170:173], 0
	v_mfma_f32_16x16x32_bf16 v[104:107], v[154:157], v[178:181], 0
	v_mfma_f32_16x16x32_bf16 v[100:103], v[162:165], v[178:181], 0
	v_mfma_f32_16x16x32_bf16 v[88:91], v[154:157], v[186:189], 0
	v_mfma_f32_16x16x32_bf16 v[84:87], v[162:165], v[186:189], 0
	v_mfma_f32_16x16x32_bf16 v[72:75], v[154:157], v[194:197], 0
	v_mfma_f32_16x16x32_bf16 v[68:71], v[162:165], v[194:197], 0
	v_mfma_f32_16x16x32_bf16 v[120:123], v[158:161], v[174:177], v[120:123]
	v_mfma_f32_16x16x32_bf16 v[116:119], v[166:169], v[174:177], v[116:119]
	v_mfma_f32_16x16x32_bf16 v[104:107], v[158:161], v[182:185], v[104:107]
	v_mfma_f32_16x16x32_bf16 v[100:103], v[166:169], v[182:185], v[100:103]
	v_mfma_f32_16x16x32_bf16 v[88:91], v[158:161], v[190:193], v[88:91]
	v_mfma_f32_16x16x32_bf16 v[84:87], v[166:169], v[190:193], v[84:87]
	v_mfma_f32_16x16x32_bf16 v[72:75], v[158:161], v[206:209], v[72:75]
	v_mfma_f32_16x16x32_bf16 v[68:71], v[166:169], v[206:209], v[68:71]
	s_setprio 0
	s_barrier
	ds_read_b128 v[170:173], v137 offset:16384
	ds_read_b128 v[174:177], v137 offset:17408
	ds_read_b128 v[178:181], v137 offset:18432
	ds_read_b128 v[182:185], v137 offset:19456
	ds_read_b128 v[186:189], v137 offset:20480
	ds_read_b128 v[190:193], v137 offset:21504
	ds_read_b128 v[194:197], v137 offset:22528
	ds_read_b128 v[206:209], v137 offset:23552
	s_mov_b32 m0, s34
	s_nop 0
	global_load_lds_dwordx4 v2, s[48:49]
	s_mov_b32 m0, s35
	s_nop 0
	global_load_lds_dwordx4 v133, s[48:49]
	s_add_u32 s80, s48, 0x20000
	s_addc_u32 s81, s49, 0
	s_mov_b32 m0, s57
	s_nop 0
	global_load_lds_dwordx4 v2, s[80:81]
	s_mov_b32 m0, s58
	s_nop 0
	global_load_lds_dwordx4 v133, s[80:81]
	s_mov_b32 m0, s33
	s_nop 0
	global_load_lds_dwordx4 v1, s[50:51]
	s_mov_b32 m0, s59
	s_nop 0
	global_load_lds_dwordx4 v132, s[50:51]
	s_waitcnt vmcnt(8)
	s_waitcnt lgkmcnt(0)
	s_barrier
	s_setprio 1
	s_waitcnt lgkmcnt(7)
	v_mfma_f32_16x16x32_bf16 v[64:67], v[138:141], v[170:173], 0
	v_mfma_f32_16x16x32_bf16 v[60:63], v[146:149], v[170:173], 0
	s_waitcnt lgkmcnt(5)
	v_mfma_f32_16x16x32_bf16 v[48:51], v[138:141], v[178:181], 0
	v_mfma_f32_16x16x32_bf16 v[44:47], v[146:149], v[178:181], 0
	s_waitcnt lgkmcnt(3)
	v_mfma_f32_16x16x32_bf16 v[32:35], v[138:141], v[186:189], 0
	v_mfma_f32_16x16x32_bf16 v[28:31], v[146:149], v[186:189], 0
	s_waitcnt lgkmcnt(1)
	v_mfma_f32_16x16x32_bf16 v[16:19], v[138:141], v[194:197], 0
	v_mfma_f32_16x16x32_bf16 v[12:15], v[146:149], v[194:197], 0
	v_mfma_f32_16x16x32_bf16 v[64:67], v[142:145], v[174:177], v[64:67]
	v_mfma_f32_16x16x32_bf16 v[60:63], v[150:153], v[174:177], v[60:63]
	v_mfma_f32_16x16x32_bf16 v[48:51], v[142:145], v[182:185], v[48:51]
	v_mfma_f32_16x16x32_bf16 v[44:47], v[150:153], v[182:185], v[44:47]
	v_mfma_f32_16x16x32_bf16 v[32:35], v[142:145], v[190:193], v[32:35]
	v_mfma_f32_16x16x32_bf16 v[28:31], v[150:153], v[190:193], v[28:31]
	s_waitcnt lgkmcnt(0)
	v_mfma_f32_16x16x32_bf16 v[16:19], v[142:145], v[206:209], v[16:19]
	v_mfma_f32_16x16x32_bf16 v[12:15], v[150:153], v[206:209], v[12:15]
	s_setprio 0
	s_setprio 1
	v_mfma_f32_16x16x32_bf16 v[56:59], v[154:157], v[170:173], 0
	v_mfma_f32_16x16x32_bf16 v[52:55], v[162:165], v[170:173], 0
	v_mfma_f32_16x16x32_bf16 v[40:43], v[154:157], v[178:181], 0
	v_mfma_f32_16x16x32_bf16 v[36:39], v[162:165], v[178:181], 0
	v_mfma_f32_16x16x32_bf16 v[24:27], v[154:157], v[186:189], 0
	v_mfma_f32_16x16x32_bf16 v[20:23], v[162:165], v[186:189], 0
	v_mfma_f32_16x16x32_bf16 v[8:11], v[154:157], v[194:197], 0
	v_mfma_f32_16x16x32_bf16 v[4:7], v[162:165], v[194:197], 0
	v_mfma_f32_16x16x32_bf16 v[56:59], v[158:161], v[174:177], v[56:59]
	v_mfma_f32_16x16x32_bf16 v[52:55], v[166:169], v[174:177], v[52:55]
	v_mfma_f32_16x16x32_bf16 v[40:43], v[158:161], v[182:185], v[40:43]
	v_mfma_f32_16x16x32_bf16 v[36:39], v[166:169], v[182:185], v[36:39]
	v_mfma_f32_16x16x32_bf16 v[24:27], v[158:161], v[190:193], v[24:27]
	v_mfma_f32_16x16x32_bf16 v[20:23], v[166:169], v[190:193], v[20:23]
	v_mfma_f32_16x16x32_bf16 v[8:11], v[158:161], v[206:209], v[8:11]
	v_mfma_f32_16x16x32_bf16 v[4:7], v[166:169], v[206:209], v[4:7]
	s_setprio 0
	s_barrier
	v_add_u32_e32 v150, 0x18000, v136
	v_add_u32_e32 v166, 0x1c000, v136
	ds_read_b128 v[138:141], v150
	ds_read_b128 v[142:145], v150 offset:1024
	ds_read_b128 v[146:149], v150 offset:2048
	ds_read_b128 v[150:153], v150 offset:3072
	ds_read_b128 v[154:157], v166
	ds_read_b128 v[158:161], v166 offset:1024
	ds_read_b128 v[162:165], v166 offset:2048
	ds_read_b128 v[166:169], v166 offset:3072
	ds_read_b128 v[170:173], v137 offset:32768
	ds_read_b128 v[174:177], v137 offset:33792
	ds_read_b128 v[178:181], v137 offset:34816
	ds_read_b128 v[182:185], v137 offset:35840
	ds_read_b128 v[186:189], v137 offset:36864
	ds_read_b128 v[190:193], v137 offset:37888
	ds_read_b128 v[194:197], v137 offset:38912
	ds_read_b128 v[206:209], v137 offset:39936
	s_add_u32 s50, s50, 0x20000
	s_addc_u32 s51, s51, 0
	s_mov_b32 m0, s60
	s_nop 0
	global_load_lds_dwordx4 v1, s[50:51]
	s_mov_b32 m0, s61
	s_nop 0
	global_load_lds_dwordx4 v132, s[50:51]
	s_waitcnt vmcnt(8)
	s_waitcnt lgkmcnt(0)
	s_barrier
	s_setprio 1
	s_waitcnt lgkmcnt(7)
	v_mfma_f32_16x16x32_bf16 v[124:127], v[138:141], v[170:173], v[124:127]
	v_mfma_f32_16x16x32_bf16 v[128:131], v[146:149], v[170:173], v[128:131]
	s_waitcnt lgkmcnt(5)
	v_mfma_f32_16x16x32_bf16 v[112:115], v[138:141], v[178:181], v[112:115]
	v_mfma_f32_16x16x32_bf16 v[108:111], v[146:149], v[178:181], v[108:111]
	s_waitcnt lgkmcnt(3)
	v_mfma_f32_16x16x32_bf16 v[96:99], v[138:141], v[186:189], v[96:99]
	v_mfma_f32_16x16x32_bf16 v[92:95], v[146:149], v[186:189], v[92:95]
	s_waitcnt lgkmcnt(1)
	v_mfma_f32_16x16x32_bf16 v[80:83], v[138:141], v[194:197], v[80:83]
	v_mfma_f32_16x16x32_bf16 v[76:79], v[146:149], v[194:197], v[76:79]
	v_mfma_f32_16x16x32_bf16 v[124:127], v[142:145], v[174:177], v[124:127]
	v_mfma_f32_16x16x32_bf16 v[128:131], v[150:153], v[174:177], v[128:131]
	v_mfma_f32_16x16x32_bf16 v[112:115], v[142:145], v[182:185], v[112:115]
	v_mfma_f32_16x16x32_bf16 v[108:111], v[150:153], v[182:185], v[108:111]
	v_mfma_f32_16x16x32_bf16 v[96:99], v[142:145], v[190:193], v[96:99]
	v_mfma_f32_16x16x32_bf16 v[92:95], v[150:153], v[190:193], v[92:95]
	s_waitcnt lgkmcnt(0)
	v_mfma_f32_16x16x32_bf16 v[80:83], v[142:145], v[206:209], v[80:83]
	v_mfma_f32_16x16x32_bf16 v[76:79], v[150:153], v[206:209], v[76:79]
	s_setprio 0
	s_setprio 1
	v_mfma_f32_16x16x32_bf16 v[120:123], v[154:157], v[170:173], v[120:123]
	v_mfma_f32_16x16x32_bf16 v[116:119], v[162:165], v[170:173], v[116:119]
	v_mfma_f32_16x16x32_bf16 v[104:107], v[154:157], v[178:181], v[104:107]
	v_mfma_f32_16x16x32_bf16 v[100:103], v[162:165], v[178:181], v[100:103]
	v_mfma_f32_16x16x32_bf16 v[88:91], v[154:157], v[186:189], v[88:91]
	v_mfma_f32_16x16x32_bf16 v[84:87], v[162:165], v[186:189], v[84:87]
	v_mfma_f32_16x16x32_bf16 v[72:75], v[154:157], v[194:197], v[72:75]
	v_mfma_f32_16x16x32_bf16 v[68:71], v[162:165], v[194:197], v[68:71]
	v_mfma_f32_16x16x32_bf16 v[120:123], v[158:161], v[174:177], v[120:123]
	v_mfma_f32_16x16x32_bf16 v[116:119], v[166:169], v[174:177], v[116:119]
	v_mfma_f32_16x16x32_bf16 v[104:107], v[158:161], v[182:185], v[104:107]
	v_mfma_f32_16x16x32_bf16 v[100:103], v[166:169], v[182:185], v[100:103]
	v_mfma_f32_16x16x32_bf16 v[88:91], v[158:161], v[190:193], v[88:91]
	v_mfma_f32_16x16x32_bf16 v[84:87], v[166:169], v[190:193], v[84:87]
	v_mfma_f32_16x16x32_bf16 v[72:75], v[158:161], v[206:209], v[72:75]
	v_mfma_f32_16x16x32_bf16 v[68:71], v[166:169], v[206:209], v[68:71]
	s_setprio 0
	s_barrier
	ds_read_b128 v[170:173], v137 offset:49152
	ds_read_b128 v[174:177], v137 offset:50176
	ds_read_b128 v[178:181], v137 offset:51200
	ds_read_b128 v[182:185], v137 offset:52224
	ds_read_b128 v[186:189], v137 offset:53248
	ds_read_b128 v[190:193], v137 offset:54272
	ds_read_b128 v[194:197], v137 offset:55296
	ds_read_b128 v[206:209], v137 offset:56320
	s_add_u32 s50, s48, 0x80
	s_addc_u32 s51, s49, 0
	s_mov_b32 m0, s63
	s_nop 0
	global_load_lds_dwordx4 v2, s[50:51]
	s_add_u32 s48, s48, 0x20080
	s_mov_b32 m0, s64
	s_nop 0
	global_load_lds_dwordx4 v133, s[50:51]
	s_addc_u32 s49, s49, 0
	s_mov_b32 m0, s67
	s_nop 0
	global_load_lds_dwordx4 v2, s[48:49]
	s_mov_b32 m0, s68
	s_nop 0
	global_load_lds_dwordx4 v133, s[48:49]
	s_mov_b32 m0, s65
	s_nop 0
	global_load_lds_dwordx4 v1, s[42:43]
	s_mov_b32 m0, s66
	s_nop 0
	global_load_lds_dwordx4 v132, s[42:43]
	s_waitcnt vmcnt(8)
	s_waitcnt lgkmcnt(0)
	s_barrier
	s_setprio 1
	s_waitcnt lgkmcnt(7)
	v_mfma_f32_16x16x32_bf16 v[64:67], v[138:141], v[170:173], v[64:67]
	v_mfma_f32_16x16x32_bf16 v[60:63], v[146:149], v[170:173], v[60:63]
	s_waitcnt lgkmcnt(5)
	v_mfma_f32_16x16x32_bf16 v[48:51], v[138:141], v[178:181], v[48:51]
	v_mfma_f32_16x16x32_bf16 v[44:47], v[146:149], v[178:181], v[44:47]
	s_waitcnt lgkmcnt(3)
	v_mfma_f32_16x16x32_bf16 v[32:35], v[138:141], v[186:189], v[32:35]
	v_mfma_f32_16x16x32_bf16 v[28:31], v[146:149], v[186:189], v[28:31]
	s_waitcnt lgkmcnt(1)
	v_mfma_f32_16x16x32_bf16 v[16:19], v[138:141], v[194:197], v[16:19]
	v_mfma_f32_16x16x32_bf16 v[12:15], v[146:149], v[194:197], v[12:15]
	v_mfma_f32_16x16x32_bf16 v[64:67], v[142:145], v[174:177], v[64:67]
	v_mfma_f32_16x16x32_bf16 v[60:63], v[150:153], v[174:177], v[60:63]
	v_mfma_f32_16x16x32_bf16 v[48:51], v[142:145], v[182:185], v[48:51]
	v_mfma_f32_16x16x32_bf16 v[44:47], v[150:153], v[182:185], v[44:47]
	v_mfma_f32_16x16x32_bf16 v[32:35], v[142:145], v[190:193], v[32:35]
	v_mfma_f32_16x16x32_bf16 v[28:31], v[150:153], v[190:193], v[28:31]
	s_waitcnt lgkmcnt(0)
	v_mfma_f32_16x16x32_bf16 v[16:19], v[142:145], v[206:209], v[16:19]
	v_mfma_f32_16x16x32_bf16 v[12:15], v[150:153], v[206:209], v[12:15]
	s_setprio 0
	s_setprio 1
	v_mfma_f32_16x16x32_bf16 v[56:59], v[154:157], v[170:173], v[56:59]
	v_mfma_f32_16x16x32_bf16 v[52:55], v[162:165], v[170:173], v[52:55]
	v_mfma_f32_16x16x32_bf16 v[40:43], v[154:157], v[178:181], v[40:43]
	v_mfma_f32_16x16x32_bf16 v[36:39], v[162:165], v[178:181], v[36:39]
	v_mfma_f32_16x16x32_bf16 v[24:27], v[154:157], v[186:189], v[24:27]
	v_mfma_f32_16x16x32_bf16 v[20:23], v[162:165], v[186:189], v[20:23]
	v_mfma_f32_16x16x32_bf16 v[8:11], v[154:157], v[194:197], v[8:11]
	v_mfma_f32_16x16x32_bf16 v[4:7], v[162:165], v[194:197], v[4:7]
	v_mfma_f32_16x16x32_bf16 v[56:59], v[158:161], v[174:177], v[56:59]
	v_mfma_f32_16x16x32_bf16 v[52:55], v[166:169], v[174:177], v[52:55]
	v_mfma_f32_16x16x32_bf16 v[40:43], v[158:161], v[182:185], v[40:43]
	v_mfma_f32_16x16x32_bf16 v[36:39], v[166:169], v[182:185], v[36:39]
	v_mfma_f32_16x16x32_bf16 v[24:27], v[158:161], v[190:193], v[24:27]
	v_mfma_f32_16x16x32_bf16 v[20:23], v[166:169], v[190:193], v[20:23]
	v_mfma_f32_16x16x32_bf16 v[8:11], v[158:161], v[206:209], v[8:11]
	v_mfma_f32_16x16x32_bf16 v[4:7], v[166:169], v[206:209], v[4:7]
	s_setprio 0
	s_barrier
	s_add_u32 s75, s75, 0x100
	s_addc_u32 s76, s76, 0
	s_add_u32 s77, s77, 0x100
	s_addc_u32 s78, s78, 0
	s_add_u32 s40, s40, 0x100
	s_addc_u32 s41, s41, 0
	s_cmp_ge_i32 s79, s62
	s_mov_b32 s42, s79
	s_cbranch_scc0 .LBB0_588
	s_branch .LBB0_589

.Lkz_2:
	s_and_b64 s[48:49], s[4:5], exec
	s_cselect_b32 s3, s31, s43
	s_cselect_b32 s27, s30, s42
	s_cselect_b32 s73, s39, s41
	s_cselect_b32 s74, s38, s40
	s_add_u32 s75, s42, 0x100
	s_addc_u32 s76, s43, 0
	s_add_u32 s77, s40, 0x100
	s_addc_u32 s78, s41, 0
	s_add_u32 s40, s42, 0x10080
	s_addc_u32 s41, s43, 0
	s_mov_b32 s42, 0
	v_add_u32_e32 v150, 0x10000, v136
	v_add_u32_e32 v166, 0x14000, v136
	ds_read_b128 v[138:141], v150
	ds_read_b128 v[142:145], v150 offset:1024
	ds_read_b128 v[146:149], v150 offset:2048
	ds_read_b128 v[150:153], v150 offset:3072
	ds_read_b128 v[154:157], v166
	ds_read_b128 v[158:161], v166 offset:1024
	ds_read_b128 v[162:165], v166 offset:2048
	ds_read_b128 v[166:169], v166 offset:3072
	s_add_i32 s79, s42, 2
	s_cmp_eq_u32 s68, s42
	s_cselect_b32 s50, s27, s75
	s_cselect_b32 s51, s3, s76
	s_cselect_b32 s48, s74, s77
	s_cselect_b32 s49, s73, s78
	s_add_u32 s42, s50, 0x80
	s_addc_u32 s43, s51, 0
	ds_read_b128 v[170:173], v137
	ds_read_b128 v[174:177], v137 offset:1024
	ds_read_b128 v[178:181], v137 offset:2048
	ds_read_b128 v[182:185], v137 offset:3072
	ds_read_b128 v[186:189], v137 offset:4096
	ds_read_b128 v[190:193], v137 offset:5120
	ds_read_b128 v[194:197], v137 offset:6144
	ds_read_b128 v[206:209], v137 offset:7168
	s_mov_b32 m0, s69
	s_nop 0
	global_load_lds_dwordx4 v1, s[40:41]
	s_mov_b32 m0, s70
	s_nop 0
	global_load_lds_dwordx4 v132, s[40:41]
	s_waitcnt vmcnt(8)
	s_waitcnt lgkmcnt(0)
	s_barrier
	s_setprio 1
	s_waitcnt lgkmcnt(7)
	v_mfma_f32_16x16x32_bf16 v[124:127], v[138:141], v[170:173], 0
	v_mfma_f32_16x16x32_bf16 v[128:131], v[146:149], v[170:173], 0
	s_waitcnt lgkmcnt(5)
	v_mfma_f32_16x16x32_bf16 v[112:115], v[138:141], v[178:181], 0
	v_mfma_f32_16x16x32_bf16 v[108:111], v[146:149], v[178:181], 0
	s_waitcnt lgkmcnt(3)
	v_mfma_f32_16x16x32_bf16 v[96:99], v[138:141], v[186:189], 0
	v_mfma_f32_16x16x32_bf16 v[92:95], v[146:149], v[186:189], 0
	s_waitcnt lgkmcnt(1)
	v_mfma_f32_16x16x32_bf16 v[80:83], v[138:141], v[194:197], 0
	v_mfma_f32_16x16x32_bf16 v[76:79], v[146:149], v[194:197], 0
	v_mfma_f32_16x16x32_bf16 v[124:127], v[142:145], v[174:177], v[124:127]
	v_mfma_f32_16x16x32_bf16 v[128:131], v[150:153], v[174:177], v[128:131]
	v_mfma_f32_16x16x32_bf16 v[112:115], v[142:145], v[182:185], v[112:115]
	v_mfma_f32_16x16x32_bf16 v[108:111], v[150:153], v[182:185], v[108:111]
	v_mfma_f32_16x16x32_bf16 v[96:99], v[142:145], v[190:193], v[96:99]
	v_mfma_f32_16x16x32_bf16 v[92:95], v[150:153], v[190:193], v[92:95]
	s_waitcnt lgkmcnt(0)
	v_mfma_f32_16x16x32_bf16 v[80:83], v[142:145], v[206:209], v[80:83]
	v_mfma_f32_16x16x32_bf16 v[76:79], v[150:153], v[206:209], v[76:79]
	s_setprio 0
	s_setprio 1
	v_mfma_f32_16x16x32_bf16 v[120:123], v[154:157], v[170:173], 0
	v_mfma_f32_16x16x32_bf16 v[116:119], v[162:165], v[170:173], 0
	v_mfma_f32_16x16x32_bf16 v[104:107], v[154:157], v[178:181], 0
	v_mfma_f32_16x16x32_bf16 v[100:103], v[162:165], v[178:181], 0
	v_mfma_f32_16x16x32_bf16 v[88:91], v[154:157], v[186:189], 0
	v_mfma_f32_16x16x32_bf16 v[84:87], v[162:165], v[186:189], 0
	v_mfma_f32_16x16x32_bf16 v[72:75], v[154:157], v[194:197], 0
	v_mfma_f32_16x16x32_bf16 v[68:71], v[162:165], v[194:197], 0
	v_mfma_f32_16x16x32_bf16 v[120:123], v[158:161], v[174:177], v[120:123]
	v_mfma_f32_16x16x32_bf16 v[116:119], v[166:169], v[174:177], v[116:119]
	v_mfma_f32_16x16x32_bf16 v[104:107], v[158:161], v[182:185], v[104:107]
	v_mfma_f32_16x16x32_bf16 v[100:103], v[166:169], v[182:185], v[100:103]
	v_mfma_f32_16x16x32_bf16 v[88:91], v[158:161], v[190:193], v[88:91]
	v_mfma_f32_16x16x32_bf16 v[84:87], v[166:169], v[190:193], v[84:87]
	v_mfma_f32_16x16x32_bf16 v[72:75], v[158:161], v[206:209], v[72:75]
	v_mfma_f32_16x16x32_bf16 v[68:71], v[166:169], v[206:209], v[68:71]
	s_setprio 0
	s_barrier
	ds_read_b128 v[170:173], v137 offset:16384
	ds_read_b128 v[174:177], v137 offset:17408
	ds_read_b128 v[178:181], v137 offset:18432
	ds_read_b128 v[182:185], v137 offset:19456
	ds_read_b128 v[186:189], v137 offset:20480
	ds_read_b128 v[190:193], v137 offset:21504
	ds_read_b128 v[194:197], v137 offset:22528
	ds_read_b128 v[206:209], v137 offset:23552
	s_mov_b32 m0, s29
	s_nop 0
	global_load_lds_dwordx4 v2, s[48:49]
	s_mov_b32 m0, s34
	s_nop 0
	global_load_lds_dwordx4 v133, s[48:49]
	s_add_u32 s80, s48, 0x10000
	s_addc_u32 s81, s49, 0
	s_mov_b32 m0, s35
	s_nop 0
	global_load_lds_dwordx4 v2, s[80:81]
	s_mov_b32 m0, s57
	s_nop 0
	global_load_lds_dwordx4 v133, s[80:81]
	s_mov_b32 m0, s0
	s_nop 0
	global_load_lds_dwordx4 v1, s[50:51]
	s_mov_b32 m0, s58
	s_nop 0
	global_load_lds_dwordx4 v132, s[50:51]
	s_waitcnt vmcnt(8)
	s_waitcnt lgkmcnt(0)
	s_barrier
	s_setprio 1
	s_waitcnt lgkmcnt(7)
	v_mfma_f32_16x16x32_bf16 v[64:67], v[138:141], v[170:173], 0
	v_mfma_f32_16x16x32_bf16 v[60:63], v[146:149], v[170:173], 0
	s_waitcnt lgkmcnt(5)
	v_mfma_f32_16x16x32_bf16 v[48:51], v[138:141], v[178:181], 0
	v_mfma_f32_16x16x32_bf16 v[44:47], v[146:149], v[178:181], 0
	s_waitcnt lgkmcnt(3)
	v_mfma_f32_16x16x32_bf16 v[32:35], v[138:141], v[186:189], 0
	v_mfma_f32_16x16x32_bf16 v[28:31], v[146:149], v[186:189], 0
	s_waitcnt lgkmcnt(1)
	v_mfma_f32_16x16x32_bf16 v[16:19], v[138:141], v[194:197], 0
	v_mfma_f32_16x16x32_bf16 v[12:15], v[146:149], v[194:197], 0
	v_mfma_f32_16x16x32_bf16 v[64:67], v[142:145], v[174:177], v[64:67]
	v_mfma_f32_16x16x32_bf16 v[60:63], v[150:153], v[174:177], v[60:63]
	v_mfma_f32_16x16x32_bf16 v[48:51], v[142:145], v[182:185], v[48:51]
	v_mfma_f32_16x16x32_bf16 v[44:47], v[150:153], v[182:185], v[44:47]
	v_mfma_f32_16x16x32_bf16 v[32:35], v[142:145], v[190:193], v[32:35]
	v_mfma_f32_16x16x32_bf16 v[28:31], v[150:153], v[190:193], v[28:31]
	s_waitcnt lgkmcnt(0)
	v_mfma_f32_16x16x32_bf16 v[16:19], v[142:145], v[206:209], v[16:19]
	v_mfma_f32_16x16x32_bf16 v[12:15], v[150:153], v[206:209], v[12:15]
	s_setprio 0
	s_setprio 1
	v_mfma_f32_16x16x32_bf16 v[56:59], v[154:157], v[170:173], 0
	v_mfma_f32_16x16x32_bf16 v[52:55], v[162:165], v[170:173], 0
	v_mfma_f32_16x16x32_bf16 v[40:43], v[154:157], v[178:181], 0
	v_mfma_f32_16x16x32_bf16 v[36:39], v[162:165], v[178:181], 0
	v_mfma_f32_16x16x32_bf16 v[24:27], v[154:157], v[186:189], 0
	v_mfma_f32_16x16x32_bf16 v[20:23], v[162:165], v[186:189], 0
	v_mfma_f32_16x16x32_bf16 v[8:11], v[154:157], v[194:197], 0
	v_mfma_f32_16x16x32_bf16 v[4:7], v[162:165], v[194:197], 0
	v_mfma_f32_16x16x32_bf16 v[56:59], v[158:161], v[174:177], v[56:59]
	v_mfma_f32_16x16x32_bf16 v[52:55], v[166:169], v[174:177], v[52:55]
	v_mfma_f32_16x16x32_bf16 v[40:43], v[158:161], v[182:185], v[40:43]
	v_mfma_f32_16x16x32_bf16 v[36:39], v[166:169], v[182:185], v[36:39]
	v_mfma_f32_16x16x32_bf16 v[24:27], v[158:161], v[190:193], v[24:27]
	v_mfma_f32_16x16x32_bf16 v[20:23], v[166:169], v[190:193], v[20:23]
	v_mfma_f32_16x16x32_bf16 v[8:11], v[158:161], v[206:209], v[8:11]
	v_mfma_f32_16x16x32_bf16 v[4:7], v[166:169], v[206:209], v[4:7]
	s_setprio 0
	s_barrier
	v_add_u32_e32 v150, 0x18000, v136
	v_add_u32_e32 v166, 0x1c000, v136
	ds_read_b128 v[138:141], v150
	ds_read_b128 v[142:145], v150 offset:1024
	ds_read_b128 v[146:149], v150 offset:2048
	ds_read_b128 v[150:153], v150 offset:3072
	ds_read_b128 v[154:157], v166
	ds_read_b128 v[158:161], v166 offset:1024
	ds_read_b128 v[162:165], v166 offset:2048
	ds_read_b128 v[166:169], v166 offset:3072
	ds_read_b128 v[170:173], v137 offset:32768
	ds_read_b128 v[174:177], v137 offset:33792
	ds_read_b128 v[178:181], v137 offset:34816
	ds_read_b128 v[182:185], v137 offset:35840
	ds_read_b128 v[186:189], v137 offset:36864
	ds_read_b128 v[190:193], v137 offset:37888
	ds_read_b128 v[194:197], v137 offset:38912
	ds_read_b128 v[206:209], v137 offset:39936
	s_add_u32 s50, s50, 0x10000
	s_addc_u32 s51, s51, 0
	s_mov_b32 m0, s59
	s_nop 0
	global_load_lds_dwordx4 v1, s[50:51]
	s_mov_b32 m0, s60
	s_nop 0
	global_load_lds_dwordx4 v132, s[50:51]
	s_waitcnt vmcnt(8)
	s_waitcnt lgkmcnt(0)
	s_barrier
	s_setprio 1
	s_waitcnt lgkmcnt(7)
	v_mfma_f32_16x16x32_bf16 v[124:127], v[138:141], v[170:173], v[124:127]
	v_mfma_f32_16x16x32_bf16 v[128:131], v[146:149], v[170:173], v[128:131]
	s_waitcnt lgkmcnt(5)
	v_mfma_f32_16x16x32_bf16 v[112:115], v[138:141], v[178:181], v[112:115]
	v_mfma_f32_16x16x32_bf16 v[108:111], v[146:149], v[178:181], v[108:111]
	s_waitcnt lgkmcnt(3)
	v_mfma_f32_16x16x32_bf16 v[96:99], v[138:141], v[186:189], v[96:99]
	v_mfma_f32_16x16x32_bf16 v[92:95], v[146:149], v[186:189], v[92:95]
	s_waitcnt lgkmcnt(1)
	v_mfma_f32_16x16x32_bf16 v[80:83], v[138:141], v[194:197], v[80:83]
	v_mfma_f32_16x16x32_bf16 v[76:79], v[146:149], v[194:197], v[76:79]
	v_mfma_f32_16x16x32_bf16 v[124:127], v[142:145], v[174:177], v[124:127]
	v_mfma_f32_16x16x32_bf16 v[128:131], v[150:153], v[174:177], v[128:131]
	v_mfma_f32_16x16x32_bf16 v[112:115], v[142:145], v[182:185], v[112:115]
	v_mfma_f32_16x16x32_bf16 v[108:111], v[150:153], v[182:185], v[108:111]
	v_mfma_f32_16x16x32_bf16 v[96:99], v[142:145], v[190:193], v[96:99]
	v_mfma_f32_16x16x32_bf16 v[92:95], v[150:153], v[190:193], v[92:95]
	s_waitcnt lgkmcnt(0)
	v_mfma_f32_16x16x32_bf16 v[80:83], v[142:145], v[206:209], v[80:83]
	v_mfma_f32_16x16x32_bf16 v[76:79], v[150:153], v[206:209], v[76:79]
	s_setprio 0
	s_setprio 1
	v_mfma_f32_16x16x32_bf16 v[120:123], v[154:157], v[170:173], v[120:123]
	v_mfma_f32_16x16x32_bf16 v[116:119], v[162:165], v[170:173], v[116:119]
	v_mfma_f32_16x16x32_bf16 v[104:107], v[154:157], v[178:181], v[104:107]
	v_mfma_f32_16x16x32_bf16 v[100:103], v[162:165], v[178:181], v[100:103]
	v_mfma_f32_16x16x32_bf16 v[88:91], v[154:157], v[186:189], v[88:91]
	v_mfma_f32_16x16x32_bf16 v[84:87], v[162:165], v[186:189], v[84:87]
	v_mfma_f32_16x16x32_bf16 v[72:75], v[154:157], v[194:197], v[72:75]
	v_mfma_f32_16x16x32_bf16 v[68:71], v[162:165], v[194:197], v[68:71]
	v_mfma_f32_16x16x32_bf16 v[120:123], v[158:161], v[174:177], v[120:123]
	v_mfma_f32_16x16x32_bf16 v[116:119], v[166:169], v[174:177], v[116:119]
	v_mfma_f32_16x16x32_bf16 v[104:107], v[158:161], v[182:185], v[104:107]
	v_mfma_f32_16x16x32_bf16 v[100:103], v[166:169], v[182:185], v[100:103]
	v_mfma_f32_16x16x32_bf16 v[88:91], v[158:161], v[190:193], v[88:91]
	v_mfma_f32_16x16x32_bf16 v[84:87], v[166:169], v[190:193], v[84:87]
	v_mfma_f32_16x16x32_bf16 v[72:75], v[158:161], v[206:209], v[72:75]
	v_mfma_f32_16x16x32_bf16 v[68:71], v[166:169], v[206:209], v[68:71]
	s_setprio 0
	s_barrier
	ds_read_b128 v[170:173], v137 offset:49152
	ds_read_b128 v[174:177], v137 offset:50176
	ds_read_b128 v[178:181], v137 offset:51200
	ds_read_b128 v[182:185], v137 offset:52224
	ds_read_b128 v[186:189], v137 offset:53248
	ds_read_b128 v[190:193], v137 offset:54272
	ds_read_b128 v[194:197], v137 offset:55296
	ds_read_b128 v[206:209], v137 offset:56320
	s_add_u32 s50, s48, 0x80
	s_addc_u32 s51, s49, 0
	s_mov_b32 m0, s62
	s_nop 0
	global_load_lds_dwordx4 v2, s[50:51]
	s_add_u32 s48, s48, 0x10080
	s_mov_b32 m0, s63
	s_nop 0
	global_load_lds_dwordx4 v133, s[50:51]
	s_addc_u32 s49, s49, 0
	s_mov_b32 m0, s66
	s_nop 0
	global_load_lds_dwordx4 v2, s[48:49]
	s_mov_b32 m0, s67
	s_nop 0
	global_load_lds_dwordx4 v133, s[48:49]
	s_mov_b32 m0, s64
	s_nop 0
	global_load_lds_dwordx4 v1, s[42:43]
	s_mov_b32 m0, s65
	s_nop 0
	global_load_lds_dwordx4 v132, s[42:43]
	s_waitcnt vmcnt(8)
	s_waitcnt lgkmcnt(0)
	s_barrier
	s_setprio 1
	s_waitcnt lgkmcnt(7)
	v_mfma_f32_16x16x32_bf16 v[64:67], v[138:141], v[170:173], v[64:67]
	v_mfma_f32_16x16x32_bf16 v[60:63], v[146:149], v[170:173], v[60:63]
	s_waitcnt lgkmcnt(5)
	v_mfma_f32_16x16x32_bf16 v[48:51], v[138:141], v[178:181], v[48:51]
	v_mfma_f32_16x16x32_bf16 v[44:47], v[146:149], v[178:181], v[44:47]
	s_waitcnt lgkmcnt(3)
	v_mfma_f32_16x16x32_bf16 v[32:35], v[138:141], v[186:189], v[32:35]
	v_mfma_f32_16x16x32_bf16 v[28:31], v[146:149], v[186:189], v[28:31]
	s_waitcnt lgkmcnt(1)
	v_mfma_f32_16x16x32_bf16 v[16:19], v[138:141], v[194:197], v[16:19]
	v_mfma_f32_16x16x32_bf16 v[12:15], v[146:149], v[194:197], v[12:15]
	v_mfma_f32_16x16x32_bf16 v[64:67], v[142:145], v[174:177], v[64:67]
	v_mfma_f32_16x16x32_bf16 v[60:63], v[150:153], v[174:177], v[60:63]
	v_mfma_f32_16x16x32_bf16 v[48:51], v[142:145], v[182:185], v[48:51]
	v_mfma_f32_16x16x32_bf16 v[44:47], v[150:153], v[182:185], v[44:47]
	v_mfma_f32_16x16x32_bf16 v[32:35], v[142:145], v[190:193], v[32:35]
	v_mfma_f32_16x16x32_bf16 v[28:31], v[150:153], v[190:193], v[28:31]
	s_waitcnt lgkmcnt(0)
	v_mfma_f32_16x16x32_bf16 v[16:19], v[142:145], v[206:209], v[16:19]
	v_mfma_f32_16x16x32_bf16 v[12:15], v[150:153], v[206:209], v[12:15]
	s_setprio 0
	s_setprio 1
	v_mfma_f32_16x16x32_bf16 v[56:59], v[154:157], v[170:173], v[56:59]
	v_mfma_f32_16x16x32_bf16 v[52:55], v[162:165], v[170:173], v[52:55]
	v_mfma_f32_16x16x32_bf16 v[40:43], v[154:157], v[178:181], v[40:43]
	v_mfma_f32_16x16x32_bf16 v[36:39], v[162:165], v[178:181], v[36:39]
	v_mfma_f32_16x16x32_bf16 v[24:27], v[154:157], v[186:189], v[24:27]
	v_mfma_f32_16x16x32_bf16 v[20:23], v[162:165], v[186:189], v[20:23]
	v_mfma_f32_16x16x32_bf16 v[8:11], v[154:157], v[194:197], v[8:11]
	v_mfma_f32_16x16x32_bf16 v[4:7], v[162:165], v[194:197], v[4:7]
	v_mfma_f32_16x16x32_bf16 v[56:59], v[158:161], v[174:177], v[56:59]
	v_mfma_f32_16x16x32_bf16 v[52:55], v[166:169], v[174:177], v[52:55]
	v_mfma_f32_16x16x32_bf16 v[40:43], v[158:161], v[182:185], v[40:43]
	v_mfma_f32_16x16x32_bf16 v[36:39], v[166:169], v[182:185], v[36:39]
	v_mfma_f32_16x16x32_bf16 v[24:27], v[158:161], v[190:193], v[24:27]
	v_mfma_f32_16x16x32_bf16 v[20:23], v[166:169], v[190:193], v[20:23]
	v_mfma_f32_16x16x32_bf16 v[8:11], v[158:161], v[206:209], v[8:11]
	v_mfma_f32_16x16x32_bf16 v[4:7], v[166:169], v[206:209], v[4:7]
	s_setprio 0
	s_barrier
	s_add_u32 s75, s75, 0x100
	s_addc_u32 s76, s76, 0
	s_add_u32 s77, s77, 0x100
	s_addc_u32 s78, s78, 0
	s_add_u32 s40, s40, 0x100
	s_addc_u32 s41, s41, 0
	s_cmp_ge_i32 s79, s61
	s_mov_b32 s42, s79
	s_cbranch_scc0 .LBB0_605
	s_branch .LBB0_606

.Lkz_3:
	s_and_b64 s[40:41], s[38:39], exec
	s_cselect_b32 s3, s25, s31
	s_cselect_b32 s21, s24, s30
	s_cselect_b32 s23, s27, s29
	s_cselect_b32 s66, s26, s28
	s_add_u32 s67, s30, 0x100
	s_addc_u32 s68, s31, 0
	s_add_u32 s69, s28, 0x100
	s_addc_u32 s70, s29, 0
	s_mov_b32 s28, 0
	v_add_u32_e32 v144, 0x10000, v154
	v_add_u32_e32 v148, 0x14000, v154
	ds_read_b128 v[132:135], v144
	ds_read_b128 v[136:139], v144 offset:1024
	ds_read_b128 v[140:143], v144 offset:2048
	ds_read_b128 v[144:147], v144 offset:3072
	ds_read_b128 v[156:159], v148
	ds_read_b128 v[160:163], v148 offset:1024
	ds_read_b128 v[164:167], v148 offset:2048
	ds_read_b128 v[168:171], v148 offset:3072
	s_add_i32 s71, s28, 2
	s_cmp_eq_u32 s14, s28
	s_cselect_b32 s40, s21, s67
	s_cselect_b32 s41, s3, s68
	s_cselect_b32 s30, s66, s69
	s_cselect_b32 s31, s23, s70
	s_add_u32 s28, s40, 0x80
	s_addc_u32 s29, s41, 0
	ds_read_b128 v[172:175], v155
	ds_read_b128 v[176:179], v155 offset:1024
	ds_read_b128 v[180:183], v155 offset:2048
	ds_read_b128 v[184:187], v155 offset:3072
	ds_read_b128 v[188:191], v155 offset:4096
	ds_read_b128 v[192:195], v155 offset:5120
	ds_read_b128 v[206:209], v155 offset:6144
	ds_read_b128 v[210:213], v155 offset:7168
	s_add_u32 s72, s67, 0x1ff80
	s_addc_u32 s73, s68, 0
	s_mov_b32 m0, s15
	s_nop 0
	global_load_lds_dwordx4 v1, s[72:73]
	s_mov_b32 m0, s34
	s_nop 0
	global_load_lds_dwordx4 v150, s[72:73]
	s_waitcnt vmcnt(8)
	s_waitcnt lgkmcnt(0)
	s_barrier
	s_setprio 1
	s_waitcnt lgkmcnt(7)
	v_mfma_f32_16x16x32_bf16 v[124:127], v[132:135], v[172:175], 0
	v_mfma_f32_16x16x32_bf16 v[128:131], v[140:143], v[172:175], 0
	s_waitcnt lgkmcnt(5)
	v_mfma_f32_16x16x32_bf16 v[112:115], v[132:135], v[180:183], 0
	v_mfma_f32_16x16x32_bf16 v[108:111], v[140:143], v[180:183], 0
	s_waitcnt lgkmcnt(3)
	v_mfma_f32_16x16x32_bf16 v[96:99], v[132:135], v[188:191], 0
	v_mfma_f32_16x16x32_bf16 v[92:95], v[140:143], v[188:191], 0
	s_waitcnt lgkmcnt(1)
	v_mfma_f32_16x16x32_bf16 v[80:83], v[132:135], v[206:209], 0
	v_mfma_f32_16x16x32_bf16 v[76:79], v[140:143], v[206:209], 0
	v_mfma_f32_16x16x32_bf16 v[124:127], v[136:139], v[176:179], v[124:127]
	v_mfma_f32_16x16x32_bf16 v[128:131], v[144:147], v[176:179], v[128:131]
	v_mfma_f32_16x16x32_bf16 v[112:115], v[136:139], v[184:187], v[112:115]
	v_mfma_f32_16x16x32_bf16 v[108:111], v[144:147], v[184:187], v[108:111]
	v_mfma_f32_16x16x32_bf16 v[96:99], v[136:139], v[192:195], v[96:99]
	v_mfma_f32_16x16x32_bf16 v[92:95], v[144:147], v[192:195], v[92:95]
	s_waitcnt lgkmcnt(0)
	v_mfma_f32_16x16x32_bf16 v[80:83], v[136:139], v[210:213], v[80:83]
	v_mfma_f32_16x16x32_bf16 v[76:79], v[144:147], v[210:213], v[76:79]
	s_setprio 0
	s_setprio 1
	v_mfma_f32_16x16x32_bf16 v[120:123], v[156:159], v[172:175], 0
	v_mfma_f32_16x16x32_bf16 v[116:119], v[164:167], v[172:175], 0
	v_mfma_f32_16x16x32_bf16 v[104:107], v[156:159], v[180:183], 0
	v_mfma_f32_16x16x32_bf16 v[100:103], v[164:167], v[180:183], 0
	v_mfma_f32_16x16x32_bf16 v[88:91], v[156:159], v[188:191], 0
	v_mfma_f32_16x16x32_bf16 v[84:87], v[164:167], v[188:191], 0
	v_mfma_f32_16x16x32_bf16 v[72:75], v[156:159], v[206:209], 0
	v_mfma_f32_16x16x32_bf16 v[68:71], v[164:167], v[206:209], 0
	v_mfma_f32_16x16x32_bf16 v[120:123], v[160:163], v[176:179], v[120:123]
	v_mfma_f32_16x16x32_bf16 v[116:119], v[168:171], v[176:179], v[116:119]
	v_mfma_f32_16x16x32_bf16 v[104:107], v[160:163], v[184:187], v[104:107]
	v_mfma_f32_16x16x32_bf16 v[100:103], v[168:171], v[184:187], v[100:103]
	v_mfma_f32_16x16x32_bf16 v[88:91], v[160:163], v[192:195], v[88:91]
	v_mfma_f32_16x16x32_bf16 v[84:87], v[168:171], v[192:195], v[84:87]
	v_mfma_f32_16x16x32_bf16 v[72:75], v[160:163], v[210:213], v[72:75]
	v_mfma_f32_16x16x32_bf16 v[68:71], v[168:171], v[210:213], v[68:71]
	s_setprio 0
	s_barrier
	ds_read_b128 v[172:175], v155 offset:16384
	ds_read_b128 v[176:179], v155 offset:17408
	ds_read_b128 v[180:183], v155 offset:18432
	ds_read_b128 v[184:187], v155 offset:19456
	ds_read_b128 v[188:191], v155 offset:20480
	ds_read_b128 v[192:195], v155 offset:21504
	ds_read_b128 v[206:209], v155 offset:22528
	ds_read_b128 v[210:213], v155 offset:23552
	s_mov_b32 m0, s50
	s_nop 0
	global_load_lds_dwordx4 v2, s[30:31]
	s_mov_b32 m0, s51
	s_nop 0
	global_load_lds_dwordx4 v151, s[30:31]
	s_add_u32 s72, s30, 0x20000
	s_addc_u32 s73, s31, 0
	s_mov_b32 m0, s55
	s_nop 0
	global_load_lds_dwordx4 v2, s[72:73]
	s_mov_b32 m0, s56
	s_nop 0
	global_load_lds_dwordx4 v151, s[72:73]
	s_mov_b32 m0, s1
	s_nop 0
	global_load_lds_dwordx4 v1, s[40:41]
	s_mov_b32 m0, s57
	s_nop 0
	global_load_lds_dwordx4 v150, s[40:41]
	s_waitcnt vmcnt(8)
	s_waitcnt lgkmcnt(0)
	s_barrier
	s_setprio 1
	s_waitcnt lgkmcnt(7)
	v_mfma_f32_16x16x32_bf16 v[64:67], v[132:135], v[172:175], 0
	v_mfma_f32_16x16x32_bf16 v[60:63], v[140:143], v[172:175], 0
	s_waitcnt lgkmcnt(5)
	v_mfma_f32_16x16x32_bf16 v[48:51], v[132:135], v[180:183], 0
	v_mfma_f32_16x16x32_bf16 v[44:47], v[140:143], v[180:183], 0
	s_waitcnt lgkmcnt(3)
	v_mfma_f32_16x16x32_bf16 v[32:35], v[132:135], v[188:191], 0
	v_mfma_f32_16x16x32_bf16 v[28:31], v[140:143], v[188:191], 0
	s_waitcnt lgkmcnt(1)
	v_mfma_f32_16x16x32_bf16 v[16:19], v[132:135], v[206:209], 0
	v_mfma_f32_16x16x32_bf16 v[12:15], v[140:143], v[206:209], 0
	v_mfma_f32_16x16x32_bf16 v[64:67], v[136:139], v[176:179], v[64:67]
	v_mfma_f32_16x16x32_bf16 v[60:63], v[144:147], v[176:179], v[60:63]
	v_mfma_f32_16x16x32_bf16 v[48:51], v[136:139], v[184:187], v[48:51]
	v_mfma_f32_16x16x32_bf16 v[44:47], v[144:147], v[184:187], v[44:47]
	v_mfma_f32_16x16x32_bf16 v[32:35], v[136:139], v[192:195], v[32:35]
	v_mfma_f32_16x16x32_bf16 v[28:31], v[144:147], v[192:195], v[28:31]
	s_waitcnt lgkmcnt(0)
	v_mfma_f32_16x16x32_bf16 v[16:19], v[136:139], v[210:213], v[16:19]
	v_mfma_f32_16x16x32_bf16 v[12:15], v[144:147], v[210:213], v[12:15]
	s_setprio 0
	s_setprio 1
	v_mfma_f32_16x16x32_bf16 v[56:59], v[156:159], v[172:175], 0
	v_mfma_f32_16x16x32_bf16 v[52:55], v[164:167], v[172:175], 0
	v_mfma_f32_16x16x32_bf16 v[40:43], v[156:159], v[180:183], 0
	v_mfma_f32_16x16x32_bf16 v[36:39], v[164:167], v[180:183], 0
	v_mfma_f32_16x16x32_bf16 v[24:27], v[156:159], v[188:191], 0
	v_mfma_f32_16x16x32_bf16 v[20:23], v[164:167], v[188:191], 0
	v_mfma_f32_16x16x32_bf16 v[8:11], v[156:159], v[206:209], 0
	v_mfma_f32_16x16x32_bf16 v[4:7], v[164:167], v[206:209], 0
	v_mfma_f32_16x16x32_bf16 v[56:59], v[160:163], v[176:179], v[56:59]
	v_mfma_f32_16x16x32_bf16 v[52:55], v[168:171], v[176:179], v[52:55]
	v_mfma_f32_16x16x32_bf16 v[40:43], v[160:163], v[184:187], v[40:43]
	v_mfma_f32_16x16x32_bf16 v[36:39], v[168:171], v[184:187], v[36:39]
	v_mfma_f32_16x16x32_bf16 v[24:27], v[160:163], v[192:195], v[24:27]
	v_mfma_f32_16x16x32_bf16 v[20:23], v[168:171], v[192:195], v[20:23]
	v_mfma_f32_16x16x32_bf16 v[8:11], v[160:163], v[210:213], v[8:11]
	v_mfma_f32_16x16x32_bf16 v[4:7], v[168:171], v[210:213], v[4:7]
	s_setprio 0
	s_barrier
	v_add_u32_e32 v144, 0x18000, v154
	v_add_u32_e32 v148, 0x1c000, v154
	ds_read_b128 v[132:135], v144
	ds_read_b128 v[136:139], v144 offset:1024
	ds_read_b128 v[140:143], v144 offset:2048
	ds_read_b128 v[144:147], v144 offset:3072
	ds_read_b128 v[156:159], v148
	ds_read_b128 v[160:163], v148 offset:1024
	ds_read_b128 v[164:167], v148 offset:2048
	ds_read_b128 v[168:171], v148 offset:3072
	ds_read_b128 v[172:175], v155 offset:32768
	ds_read_b128 v[176:179], v155 offset:33792
	ds_read_b128 v[180:183], v155 offset:34816
	ds_read_b128 v[184:187], v155 offset:35840
	ds_read_b128 v[188:191], v155 offset:36864
	ds_read_b128 v[192:195], v155 offset:37888
	ds_read_b128 v[206:209], v155 offset:38912
	ds_read_b128 v[210:213], v155 offset:39936
	s_add_u32 s40, s40, 0x20000
	s_addc_u32 s41, s41, 0
	s_mov_b32 m0, s58
	s_nop 0
	global_load_lds_dwordx4 v1, s[40:41]
	s_mov_b32 m0, s59
	s_nop 0
	global_load_lds_dwordx4 v150, s[40:41]
	s_waitcnt vmcnt(8)
	s_waitcnt lgkmcnt(0)
	s_barrier
	s_setprio 1
	s_waitcnt lgkmcnt(7)
	v_mfma_f32_16x16x32_bf16 v[124:127], v[132:135], v[172:175], v[124:127]
	v_mfma_f32_16x16x32_bf16 v[128:131], v[140:143], v[172:175], v[128:131]
	s_waitcnt lgkmcnt(5)
	v_mfma_f32_16x16x32_bf16 v[112:115], v[132:135], v[180:183], v[112:115]
	v_mfma_f32_16x16x32_bf16 v[108:111], v[140:143], v[180:183], v[108:111]
	s_waitcnt lgkmcnt(3)
	v_mfma_f32_16x16x32_bf16 v[96:99], v[132:135], v[188:191], v[96:99]
	v_mfma_f32_16x16x32_bf16 v[92:95], v[140:143], v[188:191], v[92:95]
	s_waitcnt lgkmcnt(1)
	v_mfma_f32_16x16x32_bf16 v[80:83], v[132:135], v[206:209], v[80:83]
	v_mfma_f32_16x16x32_bf16 v[76:79], v[140:143], v[206:209], v[76:79]
	v_mfma_f32_16x16x32_bf16 v[124:127], v[136:139], v[176:179], v[124:127]
	v_mfma_f32_16x16x32_bf16 v[128:131], v[144:147], v[176:179], v[128:131]
	v_mfma_f32_16x16x32_bf16 v[112:115], v[136:139], v[184:187], v[112:115]
	v_mfma_f32_16x16x32_bf16 v[108:111], v[144:147], v[184:187], v[108:111]
	v_mfma_f32_16x16x32_bf16 v[96:99], v[136:139], v[192:195], v[96:99]
	v_mfma_f32_16x16x32_bf16 v[92:95], v[144:147], v[192:195], v[92:95]
	s_waitcnt lgkmcnt(0)
	v_mfma_f32_16x16x32_bf16 v[80:83], v[136:139], v[210:213], v[80:83]
	v_mfma_f32_16x16x32_bf16 v[76:79], v[144:147], v[210:213], v[76:79]
	s_setprio 0
	s_setprio 1
	v_mfma_f32_16x16x32_bf16 v[120:123], v[156:159], v[172:175], v[120:123]
	v_mfma_f32_16x16x32_bf16 v[116:119], v[164:167], v[172:175], v[116:119]
	v_mfma_f32_16x16x32_bf16 v[104:107], v[156:159], v[180:183], v[104:107]
	v_mfma_f32_16x16x32_bf16 v[100:103], v[164:167], v[180:183], v[100:103]
	v_mfma_f32_16x16x32_bf16 v[88:91], v[156:159], v[188:191], v[88:91]
	v_mfma_f32_16x16x32_bf16 v[84:87], v[164:167], v[188:191], v[84:87]
	v_mfma_f32_16x16x32_bf16 v[72:75], v[156:159], v[206:209], v[72:75]
	v_mfma_f32_16x16x32_bf16 v[68:71], v[164:167], v[206:209], v[68:71]
	v_mfma_f32_16x16x32_bf16 v[120:123], v[160:163], v[176:179], v[120:123]
	v_mfma_f32_16x16x32_bf16 v[116:119], v[168:171], v[176:179], v[116:119]
	v_mfma_f32_16x16x32_bf16 v[104:107], v[160:163], v[184:187], v[104:107]
	v_mfma_f32_16x16x32_bf16 v[100:103], v[168:171], v[184:187], v[100:103]
	v_mfma_f32_16x16x32_bf16 v[88:91], v[160:163], v[192:195], v[88:91]
	v_mfma_f32_16x16x32_bf16 v[84:87], v[168:171], v[192:195], v[84:87]
	v_mfma_f32_16x16x32_bf16 v[72:75], v[160:163], v[210:213], v[72:75]
	v_mfma_f32_16x16x32_bf16 v[68:71], v[168:171], v[210:213], v[68:71]
	s_setprio 0
	s_barrier
	ds_read_b128 v[172:175], v155 offset:49152
	ds_read_b128 v[176:179], v155 offset:50176
	ds_read_b128 v[180:183], v155 offset:51200
	ds_read_b128 v[184:187], v155 offset:52224
	ds_read_b128 v[188:191], v155 offset:53248
	ds_read_b128 v[192:195], v155 offset:54272
	ds_read_b128 v[206:209], v155 offset:55296
	ds_read_b128 v[210:213], v155 offset:56320
	s_add_u32 s40, s30, 0x80
	s_addc_u32 s41, s31, 0
	s_mov_b32 m0, s61
	s_nop 0
	global_load_lds_dwordx4 v2, s[40:41]
	s_add_u32 s30, s30, 0x20080
	s_mov_b32 m0, s62
	s_nop 0
	global_load_lds_dwordx4 v151, s[40:41]
	s_addc_u32 s31, s31, 0
	s_mov_b32 m0, s65
	s_nop 0
	global_load_lds_dwordx4 v2, s[30:31]
	s_mov_b32 m0, s33
	s_nop 0
	global_load_lds_dwordx4 v151, s[30:31]
	s_mov_b32 m0, s63
	s_nop 0
	global_load_lds_dwordx4 v1, s[28:29]
	s_mov_b32 m0, s64
	s_nop 0
	global_load_lds_dwordx4 v150, s[28:29]
	s_waitcnt vmcnt(8)
	s_waitcnt lgkmcnt(0)
	s_barrier
	s_setprio 1
	s_waitcnt lgkmcnt(7)
	v_mfma_f32_16x16x32_bf16 v[64:67], v[132:135], v[172:175], v[64:67]
	v_mfma_f32_16x16x32_bf16 v[60:63], v[140:143], v[172:175], v[60:63]
	s_waitcnt lgkmcnt(5)
	v_mfma_f32_16x16x32_bf16 v[48:51], v[132:135], v[180:183], v[48:51]
	v_mfma_f32_16x16x32_bf16 v[44:47], v[140:143], v[180:183], v[44:47]
	s_waitcnt lgkmcnt(3)
	v_mfma_f32_16x16x32_bf16 v[32:35], v[132:135], v[188:191], v[32:35]
	v_mfma_f32_16x16x32_bf16 v[28:31], v[140:143], v[188:191], v[28:31]
	s_waitcnt lgkmcnt(1)
	v_mfma_f32_16x16x32_bf16 v[16:19], v[132:135], v[206:209], v[16:19]
	v_mfma_f32_16x16x32_bf16 v[12:15], v[140:143], v[206:209], v[12:15]
	v_mfma_f32_16x16x32_bf16 v[64:67], v[136:139], v[176:179], v[64:67]
	v_mfma_f32_16x16x32_bf16 v[60:63], v[144:147], v[176:179], v[60:63]
	v_mfma_f32_16x16x32_bf16 v[48:51], v[136:139], v[184:187], v[48:51]
	v_mfma_f32_16x16x32_bf16 v[44:47], v[144:147], v[184:187], v[44:47]
	v_mfma_f32_16x16x32_bf16 v[32:35], v[136:139], v[192:195], v[32:35]
	v_mfma_f32_16x16x32_bf16 v[28:31], v[144:147], v[192:195], v[28:31]
	s_waitcnt lgkmcnt(0)
	v_mfma_f32_16x16x32_bf16 v[16:19], v[136:139], v[210:213], v[16:19]
	v_mfma_f32_16x16x32_bf16 v[12:15], v[144:147], v[210:213], v[12:15]
	s_setprio 0
	s_setprio 1
	v_mfma_f32_16x16x32_bf16 v[56:59], v[156:159], v[172:175], v[56:59]
	v_mfma_f32_16x16x32_bf16 v[52:55], v[164:167], v[172:175], v[52:55]
	v_mfma_f32_16x16x32_bf16 v[40:43], v[156:159], v[180:183], v[40:43]
	v_mfma_f32_16x16x32_bf16 v[36:39], v[164:167], v[180:183], v[36:39]
	v_mfma_f32_16x16x32_bf16 v[24:27], v[156:159], v[188:191], v[24:27]
	v_mfma_f32_16x16x32_bf16 v[20:23], v[164:167], v[188:191], v[20:23]
	v_mfma_f32_16x16x32_bf16 v[8:11], v[156:159], v[206:209], v[8:11]
	v_mfma_f32_16x16x32_bf16 v[4:7], v[164:167], v[206:209], v[4:7]
	v_mfma_f32_16x16x32_bf16 v[56:59], v[160:163], v[176:179], v[56:59]
	v_mfma_f32_16x16x32_bf16 v[52:55], v[168:171], v[176:179], v[52:55]
	v_mfma_f32_16x16x32_bf16 v[40:43], v[160:163], v[184:187], v[40:43]
	v_mfma_f32_16x16x32_bf16 v[36:39], v[168:171], v[184:187], v[36:39]
	v_mfma_f32_16x16x32_bf16 v[24:27], v[160:163], v[192:195], v[24:27]
	v_mfma_f32_16x16x32_bf16 v[20:23], v[168:171], v[192:195], v[20:23]
	v_mfma_f32_16x16x32_bf16 v[8:11], v[160:163], v[210:213], v[8:11]
	v_mfma_f32_16x16x32_bf16 v[4:7], v[168:171], v[210:213], v[4:7]
	s_setprio 0
	s_barrier
	s_add_u32 s67, s67, 0x100
	s_addc_u32 s68, s68, 0
	s_add_u32 s69, s69, 0x100
	s_addc_u32 s70, s70, 0
	s_cmp_ge_i32 s71, s60
	s_mov_b32 s28, s71
	s_cbranch_scc0 .LBB0_622
	s_branch .LBB0_623

.Lkz_5:
	s_and_b64 s[38:39], s[4:5], exec
	s_cselect_b32 s3, s25, s31
	s_cselect_b32 s21, s24, s30
	s_cselect_b32 s65, s27, s29
	s_cselect_b32 s66, s26, s28
	s_add_u32 s67, s30, 0x100
	s_addc_u32 s68, s31, 0
	s_add_u32 s69, s28, 0x100
	s_addc_u32 s70, s29, 0
	s_add_u32 s28, s30, 0x80080
	s_addc_u32 s29, s31, 0
	s_mov_b32 s30, 0
	v_add_u32_e32 v150, 0x10000, v136
	v_add_u32_e32 v166, 0x14000, v136
	ds_read_b128 v[138:141], v150
	ds_read_b128 v[142:145], v150 offset:1024
	ds_read_b128 v[146:149], v150 offset:2048
	ds_read_b128 v[150:153], v150 offset:3072
	ds_read_b128 v[154:157], v166
	ds_read_b128 v[158:161], v166 offset:1024
	ds_read_b128 v[162:165], v166 offset:2048
	ds_read_b128 v[166:169], v166 offset:3072
	s_add_i32 s71, s30, 2
	s_cmp_eq_u32 s60, s30
	s_cselect_b32 s40, s21, s67
	s_cselect_b32 s41, s3, s68
	s_cselect_b32 s38, s66, s69
	s_cselect_b32 s39, s65, s70
	s_add_u32 s30, s40, 0x80
	s_addc_u32 s31, s41, 0
	ds_read_b128 v[170:173], v137
	ds_read_b128 v[174:177], v137 offset:1024
	ds_read_b128 v[178:181], v137 offset:2048
	ds_read_b128 v[182:185], v137 offset:3072
	ds_read_b128 v[186:189], v137 offset:4096
	ds_read_b128 v[190:193], v137 offset:5120
	ds_read_b128 v[194:197], v137 offset:6144
	ds_read_b128 v[202:205], v137 offset:7168
	s_mov_b32 m0, s61
	s_nop 0
	global_load_lds_dwordx4 v1, s[28:29]
	s_mov_b32 m0, s62
	s_nop 0
	global_load_lds_dwordx4 v132, s[28:29]
	s_waitcnt vmcnt(8)
	s_waitcnt lgkmcnt(0)
	s_barrier
	s_setprio 1
	s_waitcnt lgkmcnt(7)
	v_mfma_f32_16x16x32_bf16 v[124:127], v[138:141], v[170:173], 0
	v_mfma_f32_16x16x32_bf16 v[128:131], v[146:149], v[170:173], 0
	s_waitcnt lgkmcnt(5)
	v_mfma_f32_16x16x32_bf16 v[112:115], v[138:141], v[178:181], 0
	v_mfma_f32_16x16x32_bf16 v[108:111], v[146:149], v[178:181], 0
	s_waitcnt lgkmcnt(3)
	v_mfma_f32_16x16x32_bf16 v[96:99], v[138:141], v[186:189], 0
	v_mfma_f32_16x16x32_bf16 v[92:95], v[146:149], v[186:189], 0
	s_waitcnt lgkmcnt(1)
	v_mfma_f32_16x16x32_bf16 v[80:83], v[138:141], v[194:197], 0
	v_mfma_f32_16x16x32_bf16 v[76:79], v[146:149], v[194:197], 0
	v_mfma_f32_16x16x32_bf16 v[124:127], v[142:145], v[174:177], v[124:127]
	v_mfma_f32_16x16x32_bf16 v[128:131], v[150:153], v[174:177], v[128:131]
	v_mfma_f32_16x16x32_bf16 v[112:115], v[142:145], v[182:185], v[112:115]
	v_mfma_f32_16x16x32_bf16 v[108:111], v[150:153], v[182:185], v[108:111]
	v_mfma_f32_16x16x32_bf16 v[96:99], v[142:145], v[190:193], v[96:99]
	v_mfma_f32_16x16x32_bf16 v[92:95], v[150:153], v[190:193], v[92:95]
	s_waitcnt lgkmcnt(0)
	v_mfma_f32_16x16x32_bf16 v[80:83], v[142:145], v[202:205], v[80:83]
	v_mfma_f32_16x16x32_bf16 v[76:79], v[150:153], v[202:205], v[76:79]
	s_setprio 0
	s_setprio 1
	v_mfma_f32_16x16x32_bf16 v[120:123], v[154:157], v[170:173], 0
	v_mfma_f32_16x16x32_bf16 v[116:119], v[162:165], v[170:173], 0
	v_mfma_f32_16x16x32_bf16 v[104:107], v[154:157], v[178:181], 0
	v_mfma_f32_16x16x32_bf16 v[100:103], v[162:165], v[178:181], 0
	v_mfma_f32_16x16x32_bf16 v[88:91], v[154:157], v[186:189], 0
	v_mfma_f32_16x16x32_bf16 v[84:87], v[162:165], v[186:189], 0
	v_mfma_f32_16x16x32_bf16 v[72:75], v[154:157], v[194:197], 0
	v_mfma_f32_16x16x32_bf16 v[68:71], v[162:165], v[194:197], 0
	v_mfma_f32_16x16x32_bf16 v[120:123], v[158:161], v[174:177], v[120:123]
	v_mfma_f32_16x16x32_bf16 v[116:119], v[166:169], v[174:177], v[116:119]
	v_mfma_f32_16x16x32_bf16 v[104:107], v[158:161], v[182:185], v[104:107]
	v_mfma_f32_16x16x32_bf16 v[100:103], v[166:169], v[182:185], v[100:103]
	v_mfma_f32_16x16x32_bf16 v[88:91], v[158:161], v[190:193], v[88:91]
	v_mfma_f32_16x16x32_bf16 v[84:87], v[166:169], v[190:193], v[84:87]
	v_mfma_f32_16x16x32_bf16 v[72:75], v[158:161], v[202:205], v[72:75]
	v_mfma_f32_16x16x32_bf16 v[68:71], v[166:169], v[202:205], v[68:71]
	s_setprio 0
	s_barrier
	ds_read_b128 v[170:173], v137 offset:16384
	ds_read_b128 v[174:177], v137 offset:17408
	ds_read_b128 v[178:181], v137 offset:18432
	ds_read_b128 v[182:185], v137 offset:19456
	ds_read_b128 v[186:189], v137 offset:20480
	ds_read_b128 v[190:193], v137 offset:21504
	ds_read_b128 v[194:197], v137 offset:22528
	ds_read_b128 v[202:205], v137 offset:23552
	s_mov_b32 m0, s23
	s_nop 0
	global_load_lds_dwordx4 v2, s[38:39]
	s_mov_b32 m0, s42
	s_nop 0
	global_load_lds_dwordx4 v133, s[38:39]
	s_add_u32 s72, s38, 0x20000
	s_addc_u32 s73, s39, 0
	s_mov_b32 m0, s43
	s_nop 0
	global_load_lds_dwordx4 v2, s[72:73]
	s_mov_b32 m0, s48
	s_nop 0
	global_load_lds_dwordx4 v133, s[72:73]
	s_mov_b32 m0, s35
	s_nop 0
	global_load_lds_dwordx4 v1, s[40:41]
	s_mov_b32 m0, s49
	s_nop 0
	global_load_lds_dwordx4 v132, s[40:41]
	s_waitcnt vmcnt(8)
	s_waitcnt lgkmcnt(0)
	s_barrier
	s_setprio 1
	s_waitcnt lgkmcnt(7)
	v_mfma_f32_16x16x32_bf16 v[64:67], v[138:141], v[170:173], 0
	v_mfma_f32_16x16x32_bf16 v[60:63], v[146:149], v[170:173], 0
	s_waitcnt lgkmcnt(5)
	v_mfma_f32_16x16x32_bf16 v[48:51], v[138:141], v[178:181], 0
	v_mfma_f32_16x16x32_bf16 v[44:47], v[146:149], v[178:181], 0
	s_waitcnt lgkmcnt(3)
	v_mfma_f32_16x16x32_bf16 v[32:35], v[138:141], v[186:189], 0
	v_mfma_f32_16x16x32_bf16 v[28:31], v[146:149], v[186:189], 0
	s_waitcnt lgkmcnt(1)
	v_mfma_f32_16x16x32_bf16 v[16:19], v[138:141], v[194:197], 0
	v_mfma_f32_16x16x32_bf16 v[12:15], v[146:149], v[194:197], 0
	v_mfma_f32_16x16x32_bf16 v[64:67], v[142:145], v[174:177], v[64:67]
	v_mfma_f32_16x16x32_bf16 v[60:63], v[150:153], v[174:177], v[60:63]
	v_mfma_f32_16x16x32_bf16 v[48:51], v[142:145], v[182:185], v[48:51]
	v_mfma_f32_16x16x32_bf16 v[44:47], v[150:153], v[182:185], v[44:47]
	v_mfma_f32_16x16x32_bf16 v[32:35], v[142:145], v[190:193], v[32:35]
	v_mfma_f32_16x16x32_bf16 v[28:31], v[150:153], v[190:193], v[28:31]
	s_waitcnt lgkmcnt(0)
	v_mfma_f32_16x16x32_bf16 v[16:19], v[142:145], v[202:205], v[16:19]
	v_mfma_f32_16x16x32_bf16 v[12:15], v[150:153], v[202:205], v[12:15]
	s_setprio 0
	s_setprio 1
	v_mfma_f32_16x16x32_bf16 v[56:59], v[154:157], v[170:173], 0
	v_mfma_f32_16x16x32_bf16 v[52:55], v[162:165], v[170:173], 0
	v_mfma_f32_16x16x32_bf16 v[40:43], v[154:157], v[178:181], 0
	v_mfma_f32_16x16x32_bf16 v[36:39], v[162:165], v[178:181], 0
	v_mfma_f32_16x16x32_bf16 v[24:27], v[154:157], v[186:189], 0
	v_mfma_f32_16x16x32_bf16 v[20:23], v[162:165], v[186:189], 0
	v_mfma_f32_16x16x32_bf16 v[8:11], v[154:157], v[194:197], 0
	v_mfma_f32_16x16x32_bf16 v[4:7], v[162:165], v[194:197], 0
	v_mfma_f32_16x16x32_bf16 v[56:59], v[158:161], v[174:177], v[56:59]
	v_mfma_f32_16x16x32_bf16 v[52:55], v[166:169], v[174:177], v[52:55]
	v_mfma_f32_16x16x32_bf16 v[40:43], v[158:161], v[182:185], v[40:43]
	v_mfma_f32_16x16x32_bf16 v[36:39], v[166:169], v[182:185], v[36:39]
	v_mfma_f32_16x16x32_bf16 v[24:27], v[158:161], v[190:193], v[24:27]
	v_mfma_f32_16x16x32_bf16 v[20:23], v[166:169], v[190:193], v[20:23]
	v_mfma_f32_16x16x32_bf16 v[8:11], v[158:161], v[202:205], v[8:11]
	v_mfma_f32_16x16x32_bf16 v[4:7], v[166:169], v[202:205], v[4:7]
	s_setprio 0
	s_barrier
	v_add_u32_e32 v150, 0x18000, v136
	v_add_u32_e32 v166, 0x1c000, v136
	ds_read_b128 v[138:141], v150
	ds_read_b128 v[142:145], v150 offset:1024
	ds_read_b128 v[146:149], v150 offset:2048
	ds_read_b128 v[150:153], v150 offset:3072
	ds_read_b128 v[154:157], v166
	ds_read_b128 v[158:161], v166 offset:1024
	ds_read_b128 v[162:165], v166 offset:2048
	ds_read_b128 v[166:169], v166 offset:3072
	ds_read_b128 v[170:173], v137 offset:32768
	ds_read_b128 v[174:177], v137 offset:33792
	ds_read_b128 v[178:181], v137 offset:34816
	ds_read_b128 v[182:185], v137 offset:35840
	ds_read_b128 v[186:189], v137 offset:36864
	ds_read_b128 v[190:193], v137 offset:37888
	ds_read_b128 v[194:197], v137 offset:38912
	ds_read_b128 v[202:205], v137 offset:39936
	s_add_u32 s40, s40, 0x80000
	s_addc_u32 s41, s41, 0
	s_mov_b32 m0, s50
	s_nop 0
	global_load_lds_dwordx4 v1, s[40:41]
	s_mov_b32 m0, s51
	s_nop 0
	global_load_lds_dwordx4 v132, s[40:41]
	s_waitcnt vmcnt(8)
	s_waitcnt lgkmcnt(0)
	s_barrier
	s_setprio 1
	s_waitcnt lgkmcnt(7)
	v_mfma_f32_16x16x32_bf16 v[124:127], v[138:141], v[170:173], v[124:127]
	v_mfma_f32_16x16x32_bf16 v[128:131], v[146:149], v[170:173], v[128:131]
	s_waitcnt lgkmcnt(5)
	v_mfma_f32_16x16x32_bf16 v[112:115], v[138:141], v[178:181], v[112:115]
	v_mfma_f32_16x16x32_bf16 v[108:111], v[146:149], v[178:181], v[108:111]
	s_waitcnt lgkmcnt(3)
	v_mfma_f32_16x16x32_bf16 v[96:99], v[138:141], v[186:189], v[96:99]
	v_mfma_f32_16x16x32_bf16 v[92:95], v[146:149], v[186:189], v[92:95]
	s_waitcnt lgkmcnt(1)
	v_mfma_f32_16x16x32_bf16 v[80:83], v[138:141], v[194:197], v[80:83]
	v_mfma_f32_16x16x32_bf16 v[76:79], v[146:149], v[194:197], v[76:79]
	v_mfma_f32_16x16x32_bf16 v[124:127], v[142:145], v[174:177], v[124:127]
	v_mfma_f32_16x16x32_bf16 v[128:131], v[150:153], v[174:177], v[128:131]
	v_mfma_f32_16x16x32_bf16 v[112:115], v[142:145], v[182:185], v[112:115]
	v_mfma_f32_16x16x32_bf16 v[108:111], v[150:153], v[182:185], v[108:111]
	v_mfma_f32_16x16x32_bf16 v[96:99], v[142:145], v[190:193], v[96:99]
	v_mfma_f32_16x16x32_bf16 v[92:95], v[150:153], v[190:193], v[92:95]
	s_waitcnt lgkmcnt(0)
	v_mfma_f32_16x16x32_bf16 v[80:83], v[142:145], v[202:205], v[80:83]
	v_mfma_f32_16x16x32_bf16 v[76:79], v[150:153], v[202:205], v[76:79]
	s_setprio 0
	s_setprio 1
	v_mfma_f32_16x16x32_bf16 v[120:123], v[154:157], v[170:173], v[120:123]
	v_mfma_f32_16x16x32_bf16 v[116:119], v[162:165], v[170:173], v[116:119]
	v_mfma_f32_16x16x32_bf16 v[104:107], v[154:157], v[178:181], v[104:107]
	v_mfma_f32_16x16x32_bf16 v[100:103], v[162:165], v[178:181], v[100:103]
	v_mfma_f32_16x16x32_bf16 v[88:91], v[154:157], v[186:189], v[88:91]
	v_mfma_f32_16x16x32_bf16 v[84:87], v[162:165], v[186:189], v[84:87]
	v_mfma_f32_16x16x32_bf16 v[72:75], v[154:157], v[194:197], v[72:75]
	v_mfma_f32_16x16x32_bf16 v[68:71], v[162:165], v[194:197], v[68:71]
	v_mfma_f32_16x16x32_bf16 v[120:123], v[158:161], v[174:177], v[120:123]
	v_mfma_f32_16x16x32_bf16 v[116:119], v[166:169], v[174:177], v[116:119]
	v_mfma_f32_16x16x32_bf16 v[104:107], v[158:161], v[182:185], v[104:107]
	v_mfma_f32_16x16x32_bf16 v[100:103], v[166:169], v[182:185], v[100:103]
	v_mfma_f32_16x16x32_bf16 v[88:91], v[158:161], v[190:193], v[88:91]
	v_mfma_f32_16x16x32_bf16 v[84:87], v[166:169], v[190:193], v[84:87]
	v_mfma_f32_16x16x32_bf16 v[72:75], v[158:161], v[202:205], v[72:75]
	v_mfma_f32_16x16x32_bf16 v[68:71], v[166:169], v[202:205], v[68:71]
	s_setprio 0
	s_barrier
	ds_read_b128 v[170:173], v137 offset:49152
	ds_read_b128 v[174:177], v137 offset:50176
	ds_read_b128 v[178:181], v137 offset:51200
	ds_read_b128 v[182:185], v137 offset:52224
	ds_read_b128 v[186:189], v137 offset:53248
	ds_read_b128 v[190:193], v137 offset:54272
	ds_read_b128 v[194:197], v137 offset:55296
	ds_read_b128 v[202:205], v137 offset:56320
	s_add_u32 s40, s38, 0x80
	s_addc_u32 s41, s39, 0
	s_mov_b32 m0, s54
	s_nop 0
	global_load_lds_dwordx4 v2, s[40:41]
	s_add_u32 s38, s38, 0x20080
	s_mov_b32 m0, s55
	s_nop 0
	global_load_lds_dwordx4 v133, s[40:41]
	s_addc_u32 s39, s39, 0
	s_mov_b32 m0, s58
	s_nop 0
	global_load_lds_dwordx4 v2, s[38:39]
	s_mov_b32 m0, s59
	s_nop 0
	global_load_lds_dwordx4 v133, s[38:39]
	s_mov_b32 m0, s56
	s_nop 0
	global_load_lds_dwordx4 v1, s[30:31]
	s_mov_b32 m0, s57
	s_nop 0
	global_load_lds_dwordx4 v132, s[30:31]
	s_waitcnt vmcnt(8)
	s_waitcnt lgkmcnt(0)
	s_barrier
	s_setprio 1
	s_waitcnt lgkmcnt(7)
	v_mfma_f32_16x16x32_bf16 v[64:67], v[138:141], v[170:173], v[64:67]
	v_mfma_f32_16x16x32_bf16 v[60:63], v[146:149], v[170:173], v[60:63]
	s_waitcnt lgkmcnt(5)
	v_mfma_f32_16x16x32_bf16 v[48:51], v[138:141], v[178:181], v[48:51]
	v_mfma_f32_16x16x32_bf16 v[44:47], v[146:149], v[178:181], v[44:47]
	s_waitcnt lgkmcnt(3)
	v_mfma_f32_16x16x32_bf16 v[32:35], v[138:141], v[186:189], v[32:35]
	v_mfma_f32_16x16x32_bf16 v[28:31], v[146:149], v[186:189], v[28:31]
	s_waitcnt lgkmcnt(1)
	v_mfma_f32_16x16x32_bf16 v[16:19], v[138:141], v[194:197], v[16:19]
	v_mfma_f32_16x16x32_bf16 v[12:15], v[146:149], v[194:197], v[12:15]
	v_mfma_f32_16x16x32_bf16 v[64:67], v[142:145], v[174:177], v[64:67]
	v_mfma_f32_16x16x32_bf16 v[60:63], v[150:153], v[174:177], v[60:63]
	v_mfma_f32_16x16x32_bf16 v[48:51], v[142:145], v[182:185], v[48:51]
	v_mfma_f32_16x16x32_bf16 v[44:47], v[150:153], v[182:185], v[44:47]
	v_mfma_f32_16x16x32_bf16 v[32:35], v[142:145], v[190:193], v[32:35]
	v_mfma_f32_16x16x32_bf16 v[28:31], v[150:153], v[190:193], v[28:31]
	s_waitcnt lgkmcnt(0)
	v_mfma_f32_16x16x32_bf16 v[16:19], v[142:145], v[202:205], v[16:19]
	v_mfma_f32_16x16x32_bf16 v[12:15], v[150:153], v[202:205], v[12:15]
	s_setprio 0
	s_setprio 1
	v_mfma_f32_16x16x32_bf16 v[56:59], v[154:157], v[170:173], v[56:59]
	v_mfma_f32_16x16x32_bf16 v[52:55], v[162:165], v[170:173], v[52:55]
	v_mfma_f32_16x16x32_bf16 v[40:43], v[154:157], v[178:181], v[40:43]
	v_mfma_f32_16x16x32_bf16 v[36:39], v[162:165], v[178:181], v[36:39]
	v_mfma_f32_16x16x32_bf16 v[24:27], v[154:157], v[186:189], v[24:27]
	v_mfma_f32_16x16x32_bf16 v[20:23], v[162:165], v[186:189], v[20:23]
	v_mfma_f32_16x16x32_bf16 v[8:11], v[154:157], v[194:197], v[8:11]
	v_mfma_f32_16x16x32_bf16 v[4:7], v[162:165], v[194:197], v[4:7]
	v_mfma_f32_16x16x32_bf16 v[56:59], v[158:161], v[174:177], v[56:59]
	v_mfma_f32_16x16x32_bf16 v[52:55], v[166:169], v[174:177], v[52:55]
	v_mfma_f32_16x16x32_bf16 v[40:43], v[158:161], v[182:185], v[40:43]
	v_mfma_f32_16x16x32_bf16 v[36:39], v[166:169], v[182:185], v[36:39]
	v_mfma_f32_16x16x32_bf16 v[24:27], v[158:161], v[190:193], v[24:27]
	v_mfma_f32_16x16x32_bf16 v[20:23], v[166:169], v[190:193], v[20:23]
	v_mfma_f32_16x16x32_bf16 v[8:11], v[158:161], v[202:205], v[8:11]
	v_mfma_f32_16x16x32_bf16 v[4:7], v[166:169], v[202:205], v[4:7]
	s_setprio 0
	s_barrier
	s_add_u32 s67, s67, 0x100
	s_addc_u32 s68, s68, 0
	s_add_u32 s69, s69, 0x100
	s_addc_u32 s70, s70, 0
	s_add_u32 s28, s28, 0x100
	s_addc_u32 s29, s29, 0
	s_cmp_ge_i32 s71, s53
	s_mov_b32 s30, s71
	s_cbranch_scc0 .LBB0_1096
	s_branch .LBB0_1097

.Lkz_6:
	s_and_b64 s[38:39], s[4:5], exec
	s_cselect_b32 s21, s25, s31
	s_cselect_b32 s23, s24, s30
	s_cselect_b32 s63, s27, s29
	s_cselect_b32 s64, s26, s28
	s_add_u32 s65, s30, 0x100
	s_addc_u32 s66, s31, 0
	s_add_u32 s67, s28, 0x100
	s_addc_u32 s68, s29, 0
	s_mov_b32 s28, 0
	v_add_u32_e32 v132, 0x10000, v138
	ds_read_b128 v[140:143], v132
	ds_read_b128 v[144:147], v132 offset:1024
	ds_read_b128 v[148:151], v132 offset:2048
	ds_read_b128 v[152:155], v132 offset:3072
	v_add_u32_e32 v132, 0x14000, v138
	ds_read_b128 v[156:159], v132
	ds_read_b128 v[160:163], v132 offset:1024
	ds_read_b128 v[164:167], v132 offset:2048
	ds_read_b128 v[168:171], v132 offset:3072
	s_add_i32 s69, s28, 2
	s_cmp_eq_u32 s59, s28
	s_cselect_b32 s38, s23, s65
	s_cselect_b32 s39, s21, s66
	s_cselect_b32 s30, s64, s67
	s_cselect_b32 s31, s63, s68
	s_add_u32 s28, s38, 0x80
	s_addc_u32 s29, s39, 0
	ds_read_b128 v[172:175], v139
	ds_read_b128 v[176:179], v139 offset:1024
	ds_read_b128 v[180:183], v139 offset:2048
	ds_read_b128 v[184:187], v139 offset:3072
	ds_read_b128 v[188:191], v139 offset:4096
	ds_read_b128 v[192:195], v139 offset:5120
	ds_read_b128 v[196:199], v139 offset:6144
	ds_read_b128 v[202:205], v139 offset:7168
	s_add_u32 s70, s65, 0x7ff80
	s_addc_u32 s71, s66, 0
	s_mov_b32 m0, s60
	s_nop 0
	global_load_lds_dwordx4 v1, s[70:71]
	s_mov_b32 m0, s61
	s_nop 0
	global_load_lds_dwordx4 v134, s[70:71]
	s_waitcnt vmcnt(8)
	s_waitcnt lgkmcnt(0)
	s_barrier
	s_setprio 1
	s_waitcnt lgkmcnt(7)
	v_mfma_f32_16x16x32_bf16 v[124:127], v[140:143], v[172:175], 0
	v_mfma_f32_16x16x32_bf16 v[128:131], v[148:151], v[172:175], 0
	s_waitcnt lgkmcnt(5)
	v_mfma_f32_16x16x32_bf16 v[112:115], v[140:143], v[180:183], 0
	v_mfma_f32_16x16x32_bf16 v[108:111], v[148:151], v[180:183], 0
	s_waitcnt lgkmcnt(3)
	v_mfma_f32_16x16x32_bf16 v[96:99], v[140:143], v[188:191], 0
	v_mfma_f32_16x16x32_bf16 v[92:95], v[148:151], v[188:191], 0
	s_waitcnt lgkmcnt(1)
	v_mfma_f32_16x16x32_bf16 v[80:83], v[140:143], v[196:199], 0
	v_mfma_f32_16x16x32_bf16 v[76:79], v[148:151], v[196:199], 0
	v_mfma_f32_16x16x32_bf16 v[124:127], v[144:147], v[176:179], v[124:127]
	v_mfma_f32_16x16x32_bf16 v[128:131], v[152:155], v[176:179], v[128:131]
	v_mfma_f32_16x16x32_bf16 v[112:115], v[144:147], v[184:187], v[112:115]
	v_mfma_f32_16x16x32_bf16 v[108:111], v[152:155], v[184:187], v[108:111]
	v_mfma_f32_16x16x32_bf16 v[96:99], v[144:147], v[192:195], v[96:99]
	v_mfma_f32_16x16x32_bf16 v[92:95], v[152:155], v[192:195], v[92:95]
	s_waitcnt lgkmcnt(0)
	v_mfma_f32_16x16x32_bf16 v[80:83], v[144:147], v[202:205], v[80:83]
	v_mfma_f32_16x16x32_bf16 v[76:79], v[152:155], v[202:205], v[76:79]
	s_setprio 0
	s_setprio 1
	v_mfma_f32_16x16x32_bf16 v[120:123], v[156:159], v[172:175], 0
	v_mfma_f32_16x16x32_bf16 v[116:119], v[164:167], v[172:175], 0
	v_mfma_f32_16x16x32_bf16 v[104:107], v[156:159], v[180:183], 0
	v_mfma_f32_16x16x32_bf16 v[100:103], v[164:167], v[180:183], 0
	v_mfma_f32_16x16x32_bf16 v[88:91], v[156:159], v[188:191], 0
	v_mfma_f32_16x16x32_bf16 v[84:87], v[164:167], v[188:191], 0
	v_mfma_f32_16x16x32_bf16 v[72:75], v[156:159], v[196:199], 0
	v_mfma_f32_16x16x32_bf16 v[68:71], v[164:167], v[196:199], 0
	v_mfma_f32_16x16x32_bf16 v[120:123], v[160:163], v[176:179], v[120:123]
	v_mfma_f32_16x16x32_bf16 v[116:119], v[168:171], v[176:179], v[116:119]
	v_mfma_f32_16x16x32_bf16 v[104:107], v[160:163], v[184:187], v[104:107]
	v_mfma_f32_16x16x32_bf16 v[100:103], v[168:171], v[184:187], v[100:103]
	v_mfma_f32_16x16x32_bf16 v[88:91], v[160:163], v[192:195], v[88:91]
	v_mfma_f32_16x16x32_bf16 v[84:87], v[168:171], v[192:195], v[84:87]
	v_mfma_f32_16x16x32_bf16 v[72:75], v[160:163], v[202:205], v[72:75]
	v_mfma_f32_16x16x32_bf16 v[68:71], v[168:171], v[202:205], v[68:71]
	s_setprio 0
	s_barrier
	ds_read_b128 v[172:175], v139 offset:16384
	ds_read_b128 v[176:179], v139 offset:17408
	ds_read_b128 v[180:183], v139 offset:18432
	ds_read_b128 v[184:187], v139 offset:19456
	ds_read_b128 v[188:191], v139 offset:20480
	ds_read_b128 v[192:195], v139 offset:21504
	ds_read_b128 v[196:199], v139 offset:22528
	ds_read_b128 v[202:205], v139 offset:23552
	s_mov_b32 m0, s40
	s_nop 0
	global_load_lds_dwordx4 v2, s[30:31]
	s_mov_b32 m0, s41
	s_nop 0
	global_load_lds_dwordx4 v135, s[30:31]
	s_add_u32 s70, s30, 0x20000
	s_addc_u32 s71, s31, 0
	s_mov_b32 m0, s42
	s_nop 0
	global_load_lds_dwordx4 v2, s[70:71]
	s_mov_b32 m0, s43
	s_nop 0
	global_load_lds_dwordx4 v135, s[70:71]
	s_mov_b32 m0, s0
	s_nop 0
	global_load_lds_dwordx4 v1, s[38:39]
	s_mov_b32 m0, s48
	s_nop 0
	global_load_lds_dwordx4 v134, s[38:39]
	s_waitcnt vmcnt(8)
	s_waitcnt lgkmcnt(0)
	s_barrier
	s_setprio 1
	s_waitcnt lgkmcnt(7)
	v_mfma_f32_16x16x32_bf16 v[64:67], v[140:143], v[172:175], 0
	v_mfma_f32_16x16x32_bf16 v[60:63], v[148:151], v[172:175], 0
	s_waitcnt lgkmcnt(5)
	v_mfma_f32_16x16x32_bf16 v[48:51], v[140:143], v[180:183], 0
	v_mfma_f32_16x16x32_bf16 v[44:47], v[148:151], v[180:183], 0
	s_waitcnt lgkmcnt(3)
	v_mfma_f32_16x16x32_bf16 v[32:35], v[140:143], v[188:191], 0
	v_mfma_f32_16x16x32_bf16 v[28:31], v[148:151], v[188:191], 0
	s_waitcnt lgkmcnt(1)
	v_mfma_f32_16x16x32_bf16 v[16:19], v[140:143], v[196:199], 0
	v_mfma_f32_16x16x32_bf16 v[12:15], v[148:151], v[196:199], 0
	v_mfma_f32_16x16x32_bf16 v[64:67], v[144:147], v[176:179], v[64:67]
	v_mfma_f32_16x16x32_bf16 v[60:63], v[152:155], v[176:179], v[60:63]
	v_mfma_f32_16x16x32_bf16 v[48:51], v[144:147], v[184:187], v[48:51]
	v_mfma_f32_16x16x32_bf16 v[44:47], v[152:155], v[184:187], v[44:47]
	v_mfma_f32_16x16x32_bf16 v[32:35], v[144:147], v[192:195], v[32:35]
	v_mfma_f32_16x16x32_bf16 v[28:31], v[152:155], v[192:195], v[28:31]
	s_waitcnt lgkmcnt(0)
	v_mfma_f32_16x16x32_bf16 v[16:19], v[144:147], v[202:205], v[16:19]
	v_mfma_f32_16x16x32_bf16 v[12:15], v[152:155], v[202:205], v[12:15]
	s_setprio 0
	s_setprio 1
	v_mfma_f32_16x16x32_bf16 v[56:59], v[156:159], v[172:175], 0
	v_mfma_f32_16x16x32_bf16 v[52:55], v[164:167], v[172:175], 0
	v_mfma_f32_16x16x32_bf16 v[40:43], v[156:159], v[180:183], 0
	v_mfma_f32_16x16x32_bf16 v[36:39], v[164:167], v[180:183], 0
	v_mfma_f32_16x16x32_bf16 v[24:27], v[156:159], v[188:191], 0
	v_mfma_f32_16x16x32_bf16 v[20:23], v[164:167], v[188:191], 0
	v_mfma_f32_16x16x32_bf16 v[8:11], v[156:159], v[196:199], 0
	v_mfma_f32_16x16x32_bf16 v[4:7], v[164:167], v[196:199], 0
	v_mfma_f32_16x16x32_bf16 v[56:59], v[160:163], v[176:179], v[56:59]
	v_mfma_f32_16x16x32_bf16 v[52:55], v[168:171], v[176:179], v[52:55]
	v_mfma_f32_16x16x32_bf16 v[40:43], v[160:163], v[184:187], v[40:43]
	v_mfma_f32_16x16x32_bf16 v[36:39], v[168:171], v[184:187], v[36:39]
	v_mfma_f32_16x16x32_bf16 v[24:27], v[160:163], v[192:195], v[24:27]
	v_mfma_f32_16x16x32_bf16 v[20:23], v[168:171], v[192:195], v[20:23]
	v_mfma_f32_16x16x32_bf16 v[8:11], v[160:163], v[202:205], v[8:11]
	v_mfma_f32_16x16x32_bf16 v[4:7], v[168:171], v[202:205], v[4:7]
	s_setprio 0
	s_barrier
	v_add_u32_e32 v132, 0x18000, v138
	ds_read_b128 v[140:143], v132
	ds_read_b128 v[144:147], v132 offset:1024
	ds_read_b128 v[148:151], v132 offset:2048
	ds_read_b128 v[152:155], v132 offset:3072
	v_add_u32_e32 v132, 0x1c000, v138
	ds_read_b128 v[156:159], v132
	ds_read_b128 v[160:163], v132 offset:1024
	ds_read_b128 v[164:167], v132 offset:2048
	ds_read_b128 v[168:171], v132 offset:3072
	ds_read_b128 v[172:175], v139 offset:32768
	ds_read_b128 v[176:179], v139 offset:33792
	ds_read_b128 v[180:183], v139 offset:34816
	ds_read_b128 v[184:187], v139 offset:35840
	ds_read_b128 v[188:191], v139 offset:36864
	ds_read_b128 v[192:195], v139 offset:37888
	ds_read_b128 v[196:199], v139 offset:38912
	ds_read_b128 v[202:205], v139 offset:39936
	s_add_u32 s38, s38, 0x80000
	s_addc_u32 s39, s39, 0
	s_mov_b32 m0, s49
	s_nop 0
	global_load_lds_dwordx4 v1, s[38:39]
	s_mov_b32 m0, s50
	s_nop 0
	global_load_lds_dwordx4 v134, s[38:39]
	s_waitcnt vmcnt(8)
	s_waitcnt lgkmcnt(0)
	s_barrier
	s_setprio 1
	s_waitcnt lgkmcnt(7)
	v_mfma_f32_16x16x32_bf16 v[124:127], v[140:143], v[172:175], v[124:127]
	v_mfma_f32_16x16x32_bf16 v[128:131], v[148:151], v[172:175], v[128:131]
	s_waitcnt lgkmcnt(5)
	v_mfma_f32_16x16x32_bf16 v[112:115], v[140:143], v[180:183], v[112:115]
	v_mfma_f32_16x16x32_bf16 v[108:111], v[148:151], v[180:183], v[108:111]
	s_waitcnt lgkmcnt(3)
	v_mfma_f32_16x16x32_bf16 v[96:99], v[140:143], v[188:191], v[96:99]
	v_mfma_f32_16x16x32_bf16 v[92:95], v[148:151], v[188:191], v[92:95]
	s_waitcnt lgkmcnt(1)
	v_mfma_f32_16x16x32_bf16 v[80:83], v[140:143], v[196:199], v[80:83]
	v_mfma_f32_16x16x32_bf16 v[76:79], v[148:151], v[196:199], v[76:79]
	v_mfma_f32_16x16x32_bf16 v[124:127], v[144:147], v[176:179], v[124:127]
	v_mfma_f32_16x16x32_bf16 v[128:131], v[152:155], v[176:179], v[128:131]
	v_mfma_f32_16x16x32_bf16 v[112:115], v[144:147], v[184:187], v[112:115]
	v_mfma_f32_16x16x32_bf16 v[108:111], v[152:155], v[184:187], v[108:111]
	v_mfma_f32_16x16x32_bf16 v[96:99], v[144:147], v[192:195], v[96:99]
	v_mfma_f32_16x16x32_bf16 v[92:95], v[152:155], v[192:195], v[92:95]
	s_waitcnt lgkmcnt(0)
	v_mfma_f32_16x16x32_bf16 v[80:83], v[144:147], v[202:205], v[80:83]
	v_mfma_f32_16x16x32_bf16 v[76:79], v[152:155], v[202:205], v[76:79]
	s_setprio 0
	s_setprio 1
	v_mfma_f32_16x16x32_bf16 v[120:123], v[156:159], v[172:175], v[120:123]
	v_mfma_f32_16x16x32_bf16 v[116:119], v[164:167], v[172:175], v[116:119]
	v_mfma_f32_16x16x32_bf16 v[104:107], v[156:159], v[180:183], v[104:107]
	v_mfma_f32_16x16x32_bf16 v[100:103], v[164:167], v[180:183], v[100:103]
	v_mfma_f32_16x16x32_bf16 v[88:91], v[156:159], v[188:191], v[88:91]
	v_mfma_f32_16x16x32_bf16 v[84:87], v[164:167], v[188:191], v[84:87]
	v_mfma_f32_16x16x32_bf16 v[72:75], v[156:159], v[196:199], v[72:75]
	v_mfma_f32_16x16x32_bf16 v[68:71], v[164:167], v[196:199], v[68:71]
	v_mfma_f32_16x16x32_bf16 v[120:123], v[160:163], v[176:179], v[120:123]
	v_mfma_f32_16x16x32_bf16 v[116:119], v[168:171], v[176:179], v[116:119]
	v_mfma_f32_16x16x32_bf16 v[104:107], v[160:163], v[184:187], v[104:107]
	v_mfma_f32_16x16x32_bf16 v[100:103], v[168:171], v[184:187], v[100:103]
	v_mfma_f32_16x16x32_bf16 v[88:91], v[160:163], v[192:195], v[88:91]
	v_mfma_f32_16x16x32_bf16 v[84:87], v[168:171], v[192:195], v[84:87]
	v_mfma_f32_16x16x32_bf16 v[72:75], v[160:163], v[202:205], v[72:75]
	v_mfma_f32_16x16x32_bf16 v[68:71], v[168:171], v[202:205], v[68:71]
	s_setprio 0
	s_barrier
	ds_read_b128 v[172:175], v139 offset:49152
	ds_read_b128 v[176:179], v139 offset:50176
	ds_read_b128 v[180:183], v139 offset:51200
	ds_read_b128 v[184:187], v139 offset:52224
	ds_read_b128 v[188:191], v139 offset:53248
	ds_read_b128 v[192:195], v139 offset:54272
	ds_read_b128 v[196:199], v139 offset:55296
	ds_read_b128 v[202:205], v139 offset:56320
	s_add_u32 s38, s30, 0x80
	s_addc_u32 s39, s31, 0
	s_mov_b32 m0, s53
	s_nop 0
	global_load_lds_dwordx4 v2, s[38:39]
	s_add_u32 s30, s30, 0x20080
	s_mov_b32 m0, s54
	s_nop 0
	global_load_lds_dwordx4 v135, s[38:39]
	s_addc_u32 s31, s31, 0
	s_mov_b32 m0, s57
	s_nop 0
	global_load_lds_dwordx4 v2, s[30:31]
	s_mov_b32 m0, s58
	s_nop 0
	global_load_lds_dwordx4 v135, s[30:31]
	s_mov_b32 m0, s55
	s_nop 0
	global_load_lds_dwordx4 v1, s[28:29]
	s_mov_b32 m0, s56
	s_nop 0
	global_load_lds_dwordx4 v134, s[28:29]
	s_waitcnt vmcnt(8)
	s_waitcnt lgkmcnt(0)
	s_barrier
	s_setprio 1
	s_waitcnt lgkmcnt(7)
	v_mfma_f32_16x16x32_bf16 v[64:67], v[140:143], v[172:175], v[64:67]
	v_mfma_f32_16x16x32_bf16 v[60:63], v[148:151], v[172:175], v[60:63]
	s_waitcnt lgkmcnt(5)
	v_mfma_f32_16x16x32_bf16 v[48:51], v[140:143], v[180:183], v[48:51]
	v_mfma_f32_16x16x32_bf16 v[44:47], v[148:151], v[180:183], v[44:47]
	s_waitcnt lgkmcnt(3)
	v_mfma_f32_16x16x32_bf16 v[32:35], v[140:143], v[188:191], v[32:35]
	v_mfma_f32_16x16x32_bf16 v[28:31], v[148:151], v[188:191], v[28:31]
	s_waitcnt lgkmcnt(1)
	v_mfma_f32_16x16x32_bf16 v[16:19], v[140:143], v[196:199], v[16:19]
	v_mfma_f32_16x16x32_bf16 v[12:15], v[148:151], v[196:199], v[12:15]
	v_mfma_f32_16x16x32_bf16 v[64:67], v[144:147], v[176:179], v[64:67]
	v_mfma_f32_16x16x32_bf16 v[60:63], v[152:155], v[176:179], v[60:63]
	v_mfma_f32_16x16x32_bf16 v[48:51], v[144:147], v[184:187], v[48:51]
	v_mfma_f32_16x16x32_bf16 v[44:47], v[152:155], v[184:187], v[44:47]
	v_mfma_f32_16x16x32_bf16 v[32:35], v[144:147], v[192:195], v[32:35]
	v_mfma_f32_16x16x32_bf16 v[28:31], v[152:155], v[192:195], v[28:31]
	s_waitcnt lgkmcnt(0)
	v_mfma_f32_16x16x32_bf16 v[16:19], v[144:147], v[202:205], v[16:19]
	v_mfma_f32_16x16x32_bf16 v[12:15], v[152:155], v[202:205], v[12:15]
	s_setprio 0
	s_setprio 1
	v_mfma_f32_16x16x32_bf16 v[56:59], v[156:159], v[172:175], v[56:59]
	v_mfma_f32_16x16x32_bf16 v[52:55], v[164:167], v[172:175], v[52:55]
	v_mfma_f32_16x16x32_bf16 v[40:43], v[156:159], v[180:183], v[40:43]
	v_mfma_f32_16x16x32_bf16 v[36:39], v[164:167], v[180:183], v[36:39]
	v_mfma_f32_16x16x32_bf16 v[24:27], v[156:159], v[188:191], v[24:27]
	v_mfma_f32_16x16x32_bf16 v[20:23], v[164:167], v[188:191], v[20:23]
	v_mfma_f32_16x16x32_bf16 v[8:11], v[156:159], v[196:199], v[8:11]
	v_mfma_f32_16x16x32_bf16 v[4:7], v[164:167], v[196:199], v[4:7]
	v_mfma_f32_16x16x32_bf16 v[56:59], v[160:163], v[176:179], v[56:59]
	v_mfma_f32_16x16x32_bf16 v[52:55], v[168:171], v[176:179], v[52:55]
	v_mfma_f32_16x16x32_bf16 v[40:43], v[160:163], v[184:187], v[40:43]
	v_mfma_f32_16x16x32_bf16 v[36:39], v[168:171], v[184:187], v[36:39]
	v_mfma_f32_16x16x32_bf16 v[24:27], v[160:163], v[192:195], v[24:27]
	v_mfma_f32_16x16x32_bf16 v[20:23], v[168:171], v[192:195], v[20:23]
	v_mfma_f32_16x16x32_bf16 v[8:11], v[160:163], v[202:205], v[8:11]
	v_mfma_f32_16x16x32_bf16 v[4:7], v[168:171], v[202:205], v[4:7]
	s_setprio 0
	s_barrier
	s_add_u32 s65, s65, 0x100
	s_addc_u32 s66, s66, 0
	s_add_u32 s67, s67, 0x100
	s_addc_u32 s68, s68, 0
	s_cmp_ge_i32 s69, s52
	s_mov_b32 s28, s69
	s_cbranch_scc0 .LBB0_1237
	s_branch .LBB0_1238

.Lkz_7:
	s_and_b64 s[38:39], s[4:5], exec
	s_cselect_b32 s3, s25, s31
	s_cselect_b32 s21, s24, s30
	s_cselect_b32 s65, s27, s29
	s_cselect_b32 s66, s26, s28
	s_add_u32 s67, s30, 0x100
	s_addc_u32 s68, s31, 0
	s_add_u32 s69, s28, 0x100
	s_addc_u32 s70, s29, 0
	s_add_u32 s28, s30, 0x200080
	s_addc_u32 s29, s31, 0
	s_mov_b32 s30, 0
	v_add_u32_e32 v150, 0x10000, v136
	v_add_u32_e32 v166, 0x14000, v136
	ds_read_b128 v[138:141], v150
	ds_read_b128 v[142:145], v150 offset:1024
	ds_read_b128 v[146:149], v150 offset:2048
	ds_read_b128 v[150:153], v150 offset:3072
	ds_read_b128 v[154:157], v166
	ds_read_b128 v[158:161], v166 offset:1024
	ds_read_b128 v[162:165], v166 offset:2048
	ds_read_b128 v[166:169], v166 offset:3072
	s_add_i32 s71, s30, 2
	s_cmp_eq_u32 s60, s30
	s_cselect_b32 s40, s21, s67
	s_cselect_b32 s41, s3, s68
	s_cselect_b32 s38, s66, s69
	s_cselect_b32 s39, s65, s70
	s_add_u32 s30, s40, 0x80
	s_addc_u32 s31, s41, 0
	ds_read_b128 v[170:173], v137
	ds_read_b128 v[174:177], v137 offset:1024
	ds_read_b128 v[178:181], v137 offset:2048
	ds_read_b128 v[182:185], v137 offset:3072
	ds_read_b128 v[186:189], v137 offset:4096
	ds_read_b128 v[190:193], v137 offset:5120
	ds_read_b128 v[194:197], v137 offset:6144
	ds_read_b128 v[202:205], v137 offset:7168
	s_mov_b32 m0, s61
	s_nop 0
	global_load_lds_dwordx4 v1, s[28:29]
	s_mov_b32 m0, s62
	s_nop 0
	global_load_lds_dwordx4 v132, s[28:29]
	s_waitcnt vmcnt(8)
	s_waitcnt lgkmcnt(0)
	s_barrier
	s_setprio 1
	s_waitcnt lgkmcnt(7)
	v_mfma_f32_16x16x32_bf16 v[124:127], v[138:141], v[170:173], 0
	v_mfma_f32_16x16x32_bf16 v[128:131], v[146:149], v[170:173], 0
	s_waitcnt lgkmcnt(5)
	v_mfma_f32_16x16x32_bf16 v[112:115], v[138:141], v[178:181], 0
	v_mfma_f32_16x16x32_bf16 v[108:111], v[146:149], v[178:181], 0
	s_waitcnt lgkmcnt(3)
	v_mfma_f32_16x16x32_bf16 v[96:99], v[138:141], v[186:189], 0
	v_mfma_f32_16x16x32_bf16 v[92:95], v[146:149], v[186:189], 0
	s_waitcnt lgkmcnt(1)
	v_mfma_f32_16x16x32_bf16 v[80:83], v[138:141], v[194:197], 0
	v_mfma_f32_16x16x32_bf16 v[76:79], v[146:149], v[194:197], 0
	v_mfma_f32_16x16x32_bf16 v[124:127], v[142:145], v[174:177], v[124:127]
	v_mfma_f32_16x16x32_bf16 v[128:131], v[150:153], v[174:177], v[128:131]
	v_mfma_f32_16x16x32_bf16 v[112:115], v[142:145], v[182:185], v[112:115]
	v_mfma_f32_16x16x32_bf16 v[108:111], v[150:153], v[182:185], v[108:111]
	v_mfma_f32_16x16x32_bf16 v[96:99], v[142:145], v[190:193], v[96:99]
	v_mfma_f32_16x16x32_bf16 v[92:95], v[150:153], v[190:193], v[92:95]
	s_waitcnt lgkmcnt(0)
	v_mfma_f32_16x16x32_bf16 v[80:83], v[142:145], v[202:205], v[80:83]
	v_mfma_f32_16x16x32_bf16 v[76:79], v[150:153], v[202:205], v[76:79]
	s_setprio 0
	s_setprio 1
	v_mfma_f32_16x16x32_bf16 v[120:123], v[154:157], v[170:173], 0
	v_mfma_f32_16x16x32_bf16 v[116:119], v[162:165], v[170:173], 0
	v_mfma_f32_16x16x32_bf16 v[104:107], v[154:157], v[178:181], 0
	v_mfma_f32_16x16x32_bf16 v[100:103], v[162:165], v[178:181], 0
	v_mfma_f32_16x16x32_bf16 v[88:91], v[154:157], v[186:189], 0
	v_mfma_f32_16x16x32_bf16 v[84:87], v[162:165], v[186:189], 0
	v_mfma_f32_16x16x32_bf16 v[72:75], v[154:157], v[194:197], 0
	v_mfma_f32_16x16x32_bf16 v[68:71], v[162:165], v[194:197], 0
	v_mfma_f32_16x16x32_bf16 v[120:123], v[158:161], v[174:177], v[120:123]
	v_mfma_f32_16x16x32_bf16 v[116:119], v[166:169], v[174:177], v[116:119]
	v_mfma_f32_16x16x32_bf16 v[104:107], v[158:161], v[182:185], v[104:107]
	v_mfma_f32_16x16x32_bf16 v[100:103], v[166:169], v[182:185], v[100:103]
	v_mfma_f32_16x16x32_bf16 v[88:91], v[158:161], v[190:193], v[88:91]
	v_mfma_f32_16x16x32_bf16 v[84:87], v[166:169], v[190:193], v[84:87]
	v_mfma_f32_16x16x32_bf16 v[72:75], v[158:161], v[202:205], v[72:75]
	v_mfma_f32_16x16x32_bf16 v[68:71], v[166:169], v[202:205], v[68:71]
	s_setprio 0
	s_barrier
	ds_read_b128 v[170:173], v137 offset:16384
	ds_read_b128 v[174:177], v137 offset:17408
	ds_read_b128 v[178:181], v137 offset:18432
	ds_read_b128 v[182:185], v137 offset:19456
	ds_read_b128 v[186:189], v137 offset:20480
	ds_read_b128 v[190:193], v137 offset:21504
	ds_read_b128 v[194:197], v137 offset:22528
	ds_read_b128 v[202:205], v137 offset:23552
	s_mov_b32 m0, s23
	s_nop 0
	global_load_lds_dwordx4 v2, s[38:39]
	s_mov_b32 m0, s42
	s_nop 0
	global_load_lds_dwordx4 v133, s[38:39]
	s_add_u32 s72, s38, 0x80000
	s_addc_u32 s73, s39, 0
	s_mov_b32 m0, s43
	s_nop 0
	global_load_lds_dwordx4 v2, s[72:73]
	s_mov_b32 m0, s48
	s_nop 0
	global_load_lds_dwordx4 v133, s[72:73]
	s_mov_b32 m0, s35
	s_nop 0
	global_load_lds_dwordx4 v1, s[40:41]
	s_mov_b32 m0, s49
	s_nop 0
	global_load_lds_dwordx4 v132, s[40:41]
	s_waitcnt vmcnt(8)
	s_waitcnt lgkmcnt(0)
	s_barrier
	s_setprio 1
	s_waitcnt lgkmcnt(7)
	v_mfma_f32_16x16x32_bf16 v[64:67], v[138:141], v[170:173], 0
	v_mfma_f32_16x16x32_bf16 v[60:63], v[146:149], v[170:173], 0
	s_waitcnt lgkmcnt(5)
	v_mfma_f32_16x16x32_bf16 v[48:51], v[138:141], v[178:181], 0
	v_mfma_f32_16x16x32_bf16 v[44:47], v[146:149], v[178:181], 0
	s_waitcnt lgkmcnt(3)
	v_mfma_f32_16x16x32_bf16 v[32:35], v[138:141], v[186:189], 0
	v_mfma_f32_16x16x32_bf16 v[28:31], v[146:149], v[186:189], 0
	s_waitcnt lgkmcnt(1)
	v_mfma_f32_16x16x32_bf16 v[16:19], v[138:141], v[194:197], 0
	v_mfma_f32_16x16x32_bf16 v[12:15], v[146:149], v[194:197], 0
	v_mfma_f32_16x16x32_bf16 v[64:67], v[142:145], v[174:177], v[64:67]
	v_mfma_f32_16x16x32_bf16 v[60:63], v[150:153], v[174:177], v[60:63]
	v_mfma_f32_16x16x32_bf16 v[48:51], v[142:145], v[182:185], v[48:51]
	v_mfma_f32_16x16x32_bf16 v[44:47], v[150:153], v[182:185], v[44:47]
	v_mfma_f32_16x16x32_bf16 v[32:35], v[142:145], v[190:193], v[32:35]
	v_mfma_f32_16x16x32_bf16 v[28:31], v[150:153], v[190:193], v[28:31]
	s_waitcnt lgkmcnt(0)
	v_mfma_f32_16x16x32_bf16 v[16:19], v[142:145], v[202:205], v[16:19]
	v_mfma_f32_16x16x32_bf16 v[12:15], v[150:153], v[202:205], v[12:15]
	s_setprio 0
	s_setprio 1
	v_mfma_f32_16x16x32_bf16 v[56:59], v[154:157], v[170:173], 0
	v_mfma_f32_16x16x32_bf16 v[52:55], v[162:165], v[170:173], 0
	v_mfma_f32_16x16x32_bf16 v[40:43], v[154:157], v[178:181], 0
	v_mfma_f32_16x16x32_bf16 v[36:39], v[162:165], v[178:181], 0
	v_mfma_f32_16x16x32_bf16 v[24:27], v[154:157], v[186:189], 0
	v_mfma_f32_16x16x32_bf16 v[20:23], v[162:165], v[186:189], 0
	v_mfma_f32_16x16x32_bf16 v[8:11], v[154:157], v[194:197], 0
	v_mfma_f32_16x16x32_bf16 v[4:7], v[162:165], v[194:197], 0
	v_mfma_f32_16x16x32_bf16 v[56:59], v[158:161], v[174:177], v[56:59]
	v_mfma_f32_16x16x32_bf16 v[52:55], v[166:169], v[174:177], v[52:55]
	v_mfma_f32_16x16x32_bf16 v[40:43], v[158:161], v[182:185], v[40:43]
	v_mfma_f32_16x16x32_bf16 v[36:39], v[166:169], v[182:185], v[36:39]
	v_mfma_f32_16x16x32_bf16 v[24:27], v[158:161], v[190:193], v[24:27]
	v_mfma_f32_16x16x32_bf16 v[20:23], v[166:169], v[190:193], v[20:23]
	v_mfma_f32_16x16x32_bf16 v[8:11], v[158:161], v[202:205], v[8:11]
	v_mfma_f32_16x16x32_bf16 v[4:7], v[166:169], v[202:205], v[4:7]
	s_setprio 0
	s_barrier
	v_add_u32_e32 v150, 0x18000, v136
	v_add_u32_e32 v166, 0x1c000, v136
	ds_read_b128 v[138:141], v150
	ds_read_b128 v[142:145], v150 offset:1024
	ds_read_b128 v[146:149], v150 offset:2048
	ds_read_b128 v[150:153], v150 offset:3072
	ds_read_b128 v[154:157], v166
	ds_read_b128 v[158:161], v166 offset:1024
	ds_read_b128 v[162:165], v166 offset:2048
	ds_read_b128 v[166:169], v166 offset:3072
	ds_read_b128 v[170:173], v137 offset:32768
	ds_read_b128 v[174:177], v137 offset:33792
	ds_read_b128 v[178:181], v137 offset:34816
	ds_read_b128 v[182:185], v137 offset:35840
	ds_read_b128 v[186:189], v137 offset:36864
	ds_read_b128 v[190:193], v137 offset:37888
	ds_read_b128 v[194:197], v137 offset:38912
	ds_read_b128 v[202:205], v137 offset:39936
	s_add_u32 s40, s40, 0x200000
	s_addc_u32 s41, s41, 0
	s_mov_b32 m0, s50
	s_nop 0
	global_load_lds_dwordx4 v1, s[40:41]
	s_mov_b32 m0, s51
	s_nop 0
	global_load_lds_dwordx4 v132, s[40:41]
	s_waitcnt vmcnt(8)
	s_waitcnt lgkmcnt(0)
	s_barrier
	s_setprio 1
	s_waitcnt lgkmcnt(7)
	v_mfma_f32_16x16x32_bf16 v[124:127], v[138:141], v[170:173], v[124:127]
	v_mfma_f32_16x16x32_bf16 v[128:131], v[146:149], v[170:173], v[128:131]
	s_waitcnt lgkmcnt(5)
	v_mfma_f32_16x16x32_bf16 v[112:115], v[138:141], v[178:181], v[112:115]
	v_mfma_f32_16x16x32_bf16 v[108:111], v[146:149], v[178:181], v[108:111]
	s_waitcnt lgkmcnt(3)
	v_mfma_f32_16x16x32_bf16 v[96:99], v[138:141], v[186:189], v[96:99]
	v_mfma_f32_16x16x32_bf16 v[92:95], v[146:149], v[186:189], v[92:95]
	s_waitcnt lgkmcnt(1)
	v_mfma_f32_16x16x32_bf16 v[80:83], v[138:141], v[194:197], v[80:83]
	v_mfma_f32_16x16x32_bf16 v[76:79], v[146:149], v[194:197], v[76:79]
	v_mfma_f32_16x16x32_bf16 v[124:127], v[142:145], v[174:177], v[124:127]
	v_mfma_f32_16x16x32_bf16 v[128:131], v[150:153], v[174:177], v[128:131]
	v_mfma_f32_16x16x32_bf16 v[112:115], v[142:145], v[182:185], v[112:115]
	v_mfma_f32_16x16x32_bf16 v[108:111], v[150:153], v[182:185], v[108:111]
	v_mfma_f32_16x16x32_bf16 v[96:99], v[142:145], v[190:193], v[96:99]
	v_mfma_f32_16x16x32_bf16 v[92:95], v[150:153], v[190:193], v[92:95]
	s_waitcnt lgkmcnt(0)
	v_mfma_f32_16x16x32_bf16 v[80:83], v[142:145], v[202:205], v[80:83]
	v_mfma_f32_16x16x32_bf16 v[76:79], v[150:153], v[202:205], v[76:79]
	s_setprio 0
	s_setprio 1
	v_mfma_f32_16x16x32_bf16 v[120:123], v[154:157], v[170:173], v[120:123]
	v_mfma_f32_16x16x32_bf16 v[116:119], v[162:165], v[170:173], v[116:119]
	v_mfma_f32_16x16x32_bf16 v[104:107], v[154:157], v[178:181], v[104:107]
	v_mfma_f32_16x16x32_bf16 v[100:103], v[162:165], v[178:181], v[100:103]
	v_mfma_f32_16x16x32_bf16 v[88:91], v[154:157], v[186:189], v[88:91]
	v_mfma_f32_16x16x32_bf16 v[84:87], v[162:165], v[186:189], v[84:87]
	v_mfma_f32_16x16x32_bf16 v[72:75], v[154:157], v[194:197], v[72:75]
	v_mfma_f32_16x16x32_bf16 v[68:71], v[162:165], v[194:197], v[68:71]
	v_mfma_f32_16x16x32_bf16 v[120:123], v[158:161], v[174:177], v[120:123]
	v_mfma_f32_16x16x32_bf16 v[116:119], v[166:169], v[174:177], v[116:119]
	v_mfma_f32_16x16x32_bf16 v[104:107], v[158:161], v[182:185], v[104:107]
	v_mfma_f32_16x16x32_bf16 v[100:103], v[166:169], v[182:185], v[100:103]
	v_mfma_f32_16x16x32_bf16 v[88:91], v[158:161], v[190:193], v[88:91]
	v_mfma_f32_16x16x32_bf16 v[84:87], v[166:169], v[190:193], v[84:87]
	v_mfma_f32_16x16x32_bf16 v[72:75], v[158:161], v[202:205], v[72:75]
	v_mfma_f32_16x16x32_bf16 v[68:71], v[166:169], v[202:205], v[68:71]
	s_setprio 0
	s_barrier
	ds_read_b128 v[170:173], v137 offset:49152
	ds_read_b128 v[174:177], v137 offset:50176
	ds_read_b128 v[178:181], v137 offset:51200
	ds_read_b128 v[182:185], v137 offset:52224
	ds_read_b128 v[186:189], v137 offset:53248
	ds_read_b128 v[190:193], v137 offset:54272
	ds_read_b128 v[194:197], v137 offset:55296
	ds_read_b128 v[202:205], v137 offset:56320
	s_add_u32 s40, s38, 0x80
	s_addc_u32 s41, s39, 0
	s_mov_b32 m0, s54
	s_nop 0
	global_load_lds_dwordx4 v2, s[40:41]
	s_add_u32 s38, s38, 0x80080
	s_mov_b32 m0, s55
	s_nop 0
	global_load_lds_dwordx4 v133, s[40:41]
	s_addc_u32 s39, s39, 0
	s_mov_b32 m0, s58
	s_nop 0
	global_load_lds_dwordx4 v2, s[38:39]
	s_mov_b32 m0, s59
	s_nop 0
	global_load_lds_dwordx4 v133, s[38:39]
	s_mov_b32 m0, s56
	s_nop 0
	global_load_lds_dwordx4 v1, s[30:31]
	s_mov_b32 m0, s57
	s_nop 0
	global_load_lds_dwordx4 v132, s[30:31]
	s_waitcnt vmcnt(8)
	s_waitcnt lgkmcnt(0)
	s_barrier
	s_setprio 1
	s_waitcnt lgkmcnt(7)
	v_mfma_f32_16x16x32_bf16 v[64:67], v[138:141], v[170:173], v[64:67]
	v_mfma_f32_16x16x32_bf16 v[60:63], v[146:149], v[170:173], v[60:63]
	s_waitcnt lgkmcnt(5)
	v_mfma_f32_16x16x32_bf16 v[48:51], v[138:141], v[178:181], v[48:51]
	v_mfma_f32_16x16x32_bf16 v[44:47], v[146:149], v[178:181], v[44:47]
	s_waitcnt lgkmcnt(3)
	v_mfma_f32_16x16x32_bf16 v[32:35], v[138:141], v[186:189], v[32:35]
	v_mfma_f32_16x16x32_bf16 v[28:31], v[146:149], v[186:189], v[28:31]
	s_waitcnt lgkmcnt(1)
	v_mfma_f32_16x16x32_bf16 v[16:19], v[138:141], v[194:197], v[16:19]
	v_mfma_f32_16x16x32_bf16 v[12:15], v[146:149], v[194:197], v[12:15]
	v_mfma_f32_16x16x32_bf16 v[64:67], v[142:145], v[174:177], v[64:67]
	v_mfma_f32_16x16x32_bf16 v[60:63], v[150:153], v[174:177], v[60:63]
	v_mfma_f32_16x16x32_bf16 v[48:51], v[142:145], v[182:185], v[48:51]
	v_mfma_f32_16x16x32_bf16 v[44:47], v[150:153], v[182:185], v[44:47]
	v_mfma_f32_16x16x32_bf16 v[32:35], v[142:145], v[190:193], v[32:35]
	v_mfma_f32_16x16x32_bf16 v[28:31], v[150:153], v[190:193], v[28:31]
	s_waitcnt lgkmcnt(0)
	v_mfma_f32_16x16x32_bf16 v[16:19], v[142:145], v[202:205], v[16:19]
	v_mfma_f32_16x16x32_bf16 v[12:15], v[150:153], v[202:205], v[12:15]
	s_setprio 0
	s_setprio 1
	v_mfma_f32_16x16x32_bf16 v[56:59], v[154:157], v[170:173], v[56:59]
	v_mfma_f32_16x16x32_bf16 v[52:55], v[162:165], v[170:173], v[52:55]
	v_mfma_f32_16x16x32_bf16 v[40:43], v[154:157], v[178:181], v[40:43]
	v_mfma_f32_16x16x32_bf16 v[36:39], v[162:165], v[178:181], v[36:39]
	v_mfma_f32_16x16x32_bf16 v[24:27], v[154:157], v[186:189], v[24:27]
	v_mfma_f32_16x16x32_bf16 v[20:23], v[162:165], v[186:189], v[20:23]
	v_mfma_f32_16x16x32_bf16 v[8:11], v[154:157], v[194:197], v[8:11]
	v_mfma_f32_16x16x32_bf16 v[4:7], v[162:165], v[194:197], v[4:7]
	v_mfma_f32_16x16x32_bf16 v[56:59], v[158:161], v[174:177], v[56:59]
	v_mfma_f32_16x16x32_bf16 v[52:55], v[166:169], v[174:177], v[52:55]
	v_mfma_f32_16x16x32_bf16 v[40:43], v[158:161], v[182:185], v[40:43]
	v_mfma_f32_16x16x32_bf16 v[36:39], v[166:169], v[182:185], v[36:39]
	v_mfma_f32_16x16x32_bf16 v[24:27], v[158:161], v[190:193], v[24:27]
	v_mfma_f32_16x16x32_bf16 v[20:23], v[166:169], v[190:193], v[20:23]
	v_mfma_f32_16x16x32_bf16 v[8:11], v[158:161], v[202:205], v[8:11]
	v_mfma_f32_16x16x32_bf16 v[4:7], v[166:169], v[202:205], v[4:7]
	s_setprio 0
	s_barrier
	s_add_u32 s67, s67, 0x100
	s_addc_u32 s68, s68, 0
	s_add_u32 s69, s69, 0x100
	s_addc_u32 s70, s70, 0
	s_add_u32 s28, s28, 0x100
	s_addc_u32 s29, s29, 0
	s_cmp_ge_i32 s71, s53
	s_mov_b32 s30, s71
	s_cbranch_scc0 .LBB0_1309
	s_branch .LBB0_1310
